# scan loop v5: 4-deep prefetch ring of the B*u operand only; the D*u operands rebuilt from it with v_permlane32_swap (two global loads per tile less)
# baseline (speedup 1.0000x reference)
.LBB0_563:
	s_and_b32 s13, s6, 0xff
	s_lshl_b32 s0, s13, 2
	v_mov_b32_e32 v0, s0
	global_load_dword v2, v0, s[38:39]
	s_lshl_b32 s4, s13, 6
	v_or_b32_e32 v0, s4, v174
	v_lshlrev_b32_e32 v3, 2, v0
	global_load_dword v21, v3, s[58:59]
	global_load_dword v20, v3, s[36:37]
	s_and_b32 s2, s10, 0x1800
	v_or_b32_e32 v1, s2, v182
	v_lshlrev_b32_e32 v1, 3, v1
	s_bfe_u32 s0, s12, 0x70001
	v_and_b32_e32 v1, 0xc180, v1
	v_or_b32_e32 v1, s0, v1
	v_lshlrev_b32_e32 v132, 10, v1
	v_lshl_add_u64 v[150:151], v[144:145], 0, v[132:133]
	v_lshl_add_u64 v[152:153], v[146:147], 0, v[132:133]
	v_lshl_add_u64 v[154:155], v[148:149], 0, v[132:133]
	v_lshlrev_b32_e32 v132, 6, v0
	v_lshl_add_u64 v[0:1], v[136:137], 0, v[132:133]
	global_load_dwordx4 v[4:7], v[0:1], off
	global_load_dwordx4 v[8:11], v[0:1], off offset:16
	v_lshl_add_u64 v[0:1], v[134:135], 0, v[132:133]
	global_load_dwordx4 v[12:15], v[0:1], off
	global_load_dwordx4 v[16:19], v[0:1], off offset:16
	v_or_b32_e32 v0, s4, v173
	v_lshlrev_b32_e32 v22, 2, v0
	v_or_b32_e32 v132, 0x800, v132
	s_bfe_u32 s16, s6, 0x70001
	v_mov_b32_e32 v188, 0
	v_mov_b32_e32 v189, v133
	s_waitcnt vmcnt(6)
	v_mul_f32_e32 v0, 0x3fb8aa3b, v2
	v_exp_f32_e32 v0, v0
	global_load_dword v2, v22, s[58:59]
	global_load_dword v1, v22, s[36:37]
	s_waitcnt vmcnt(7)
	v_mov_b32_e32 v22, v21
	v_mov_b32_e32 v25, v21
	v_mul_f32_e32 v23, v0, v21
	s_waitcnt vmcnt(6)
	v_mul_f32_e32 v24, v0, v20
	v_mul_f32_e32 v23, 0x3fb8aa3b, v23
	v_mul_f32_e32 v24, 0.15915494, v24
	v_exp_f32_e32 v23, v23
	v_sin_f32_e32 v26, v24
	v_cos_f32_e32 v24, v24
	v_mov_b32_e32 v27, v20
	v_mul_f32_e32 v28, v23, v26
	v_fma_f32 v29, v23, v24, -1.0
	v_mov_b32_e32 v24, v28
	v_mov_b32_e32 v26, v29
	v_pk_mul_f32 v[30:31], v[20:21], v[28:29]
	v_pk_mul_f32 v[22:23], v[22:23], v[24:25] op_sel_hi:[0,1]
	v_pk_mul_f32 v[20:21], v[20:21], v[26:27] op_sel_hi:[0,1]
	v_add_f32_e32 v28, v30, v31
	v_add_f32_e32 v21, v23, v21
	v_sub_f32_e32 v22, v22, v20
	v_div_scale_f32 v20, s[0:1], v21, v21, v28
	v_div_scale_f32 v24, s[0:1], v21, v21, v22
	v_rcp_f32_e32 v25, v20
	v_rcp_f32_e32 v26, v24
	v_div_scale_f32 v23, vcc, v28, v21, v28
	v_fma_f32 v29, -v20, v25, 1.0
	v_fma_f32 v30, -v24, v26, 1.0
	v_fmac_f32_e32 v25, v29, v25
	v_div_scale_f32 v27, s[0:1], v22, v21, v22
	v_fmac_f32_e32 v26, v30, v26
	v_mul_f32_e32 v29, v23, v25
	v_mul_f32_e32 v30, v27, v26
	v_fma_f32 v31, -v20, v29, v23
	v_fma_f32 v32, -v24, v30, v27
	v_fmac_f32_e32 v29, v31, v25
	v_fmac_f32_e32 v30, v32, v26
	v_fma_f32 v20, -v20, v29, v23
	v_fma_f32 v23, -v24, v30, v27
	v_div_fmas_f32 v20, v20, v25, v29
	s_mov_b64 vcc, s[0:1]
	v_div_fmas_f32 v23, v23, v26, v30
	v_div_fixup_f32 v22, v23, v21, v22
	v_div_fixup_f32 v20, v20, v21, v28
	s_waitcnt vmcnt(5)
	v_pk_mul_f32 v[24:25], v[4:5], v[22:23] op_sel_hi:[1,0]
	v_pk_mul_f32 v[26:27], v[6:7], v[22:23] op_sel_hi:[1,0]
	s_waitcnt vmcnt(4)
	v_pk_mul_f32 v[28:29], v[8:9], v[22:23] op_sel_hi:[1,0]
	v_pk_mul_f32 v[30:31], v[10:11], v[22:23] op_sel_hi:[1,0]
	s_waitcnt vmcnt(3)
	v_pk_mul_f32 v[32:33], v[12:13], v[22:23] op_sel_hi:[1,0]
	v_pk_mul_f32 v[34:35], v[14:15], v[22:23] op_sel_hi:[1,0]
	s_waitcnt vmcnt(2)
	v_pk_mul_f32 v[36:37], v[16:17], v[22:23] op_sel_hi:[1,0]
	v_pk_mul_f32 v[22:23], v[18:19], v[22:23] op_sel_hi:[1,0]
	v_pk_fma_f32 v[14:15], v[14:15], v[20:21], v[26:27] op_sel_hi:[1,0,1] neg_lo:[0,0,1] neg_hi:[0,0,1]
	v_pk_fma_f32 v[12:13], v[12:13], v[20:21], v[24:25] op_sel_hi:[1,0,1] neg_lo:[0,0,1] neg_hi:[0,0,1]
	v_pk_fma_f32 v[18:19], v[18:19], v[20:21], v[30:31] op_sel_hi:[1,0,1] neg_lo:[0,0,1] neg_hi:[0,0,1]
	v_pk_fma_f32 v[16:17], v[16:17], v[20:21], v[28:29] op_sel_hi:[1,0,1] neg_lo:[0,0,1] neg_hi:[0,0,1]
	v_pk_fma_f32 v[6:7], v[6:7], v[20:21], v[34:35] op_sel_hi:[1,0,1]
	v_pk_fma_f32 v[4:5], v[4:5], v[20:21], v[32:33] op_sel_hi:[1,0,1]
	v_pk_fma_f32 v[10:11], v[10:11], v[20:21], v[22:23] op_sel_hi:[1,0,1]
	v_pk_fma_f32 v[8:9], v[8:9], v[20:21], v[36:37] op_sel_hi:[1,0,1]
	v_cvt_pk_bf16_f32 v104, v12, v13
	v_cvt_pk_bf16_f32 v105, v14, v15
	v_cvt_pk_bf16_f32 v106, v16, v17
	v_cvt_pk_bf16_f32 v107, v18, v19
	v_cvt_pk_bf16_f32 v92, v4, v5
	v_cvt_pk_bf16_f32 v93, v6, v7
	s_nop 0
	v_cvt_pk_bf16_f32 v94, v8, v9
	v_cvt_pk_bf16_f32 v95, v10, v11
	v_lshl_or_b32 v58, s13, 12, v183
	v_mov_b32_e32 v59, 0
	v_lshl_add_u64 v[60:61], v[138:139], 0, v[58:59]
	v_lshl_add_u64 v[62:63], v[140:141], 0, v[58:59]
	global_load_dwordx4 v[196:199], v[60:61], off
	global_load_dwordx4 v[200:203], v[62:63], off
	global_load_dwordx4 v[204:207], v[60:61], off offset:32
	global_load_dwordx4 v[208:211], v[62:63], off offset:32
	global_load_dwordx4 v[212:215], v[60:61], off offset:64
	global_load_dwordx4 v[216:219], v[62:63], off offset:64
	global_load_dwordx4 v[220:223], v[60:61], off offset:96
	global_load_dwordx4 v[224:227], v[62:63], off offset:96
	global_load_dwordx4 v[228:231], v[60:61], off offset:128
	global_load_dwordx4 v[232:235], v[62:63], off offset:128
	global_load_dwordx4 v[236:239], v[60:61], off offset:160
	global_load_dwordx4 v[240:243], v[62:63], off offset:160
	global_load_dwordx4 v[244:247], v[60:61], off offset:192
	global_load_dwordx4 v[40:43], v[62:63], off offset:192
	global_load_dwordx4 v[44:47], v[60:61], off offset:224
	global_load_dwordx4 v[48:51], v[62:63], off offset:224
	global_load_dword v21, v3, s[58:59] offset:128
	global_load_dword v20, v3, s[36:37] offset:128
	v_lshl_add_u64 v[12:13], v[136:137], 0, v[132:133]
	v_lshl_add_u64 v[22:23], v[134:135], 0, v[132:133]
	global_load_dwordx4 v[4:7], v[12:13], off
	global_load_dwordx4 v[8:11], v[12:13], off offset:16
	s_nop 0
	global_load_dwordx4 v[12:15], v[22:23], off
	global_load_dwordx4 v[16:19], v[22:23], off offset:16
	v_lshl_or_b32 v132, s13, 12, v183
	v_lshl_add_u64 v[22:23], v[138:139], 0, v[132:133]
	s_waitcnt vmcnt(7)
	v_mul_f32_e32 v2, v2, v0
	v_mul_f32_e32 v2, 0x3fb8aa3b, v2
	v_exp_f32_e32 v2, v2
	s_waitcnt vmcnt(5)
	v_mul_f32_e32 v3, v0, v21
	s_waitcnt vmcnt(4)
	v_mul_f32_e32 v25, v0, v20
	v_mul_f32_e32 v3, 0x3fb8aa3b, v3
	v_mul_f32_e32 v25, 0.15915494, v25
	v_exp_f32_e32 v3, v3
	v_sin_f32_e32 v26, v25
	v_cos_f32_e32 v25, v25
	v_mov_b32_e32 v24, v21
	v_mov_b32_e32 v27, v21
	v_mul_f32_e32 v30, v3, v26
	v_fma_f32 v31, v3, v25, -1.0
	v_mov_b32_e32 v29, v20
	v_mov_b32_e32 v26, v30
	v_mov_b32_e32 v28, v31
	v_pk_mul_f32 v[32:33], v[20:21], v[30:31]
	v_pk_mul_f32 v[24:25], v[24:25], v[26:27] op_sel_hi:[0,1]
	v_pk_mul_f32 v[20:21], v[20:21], v[28:29] op_sel_hi:[0,1]
	v_add_f32_e32 v3, v32, v33
	v_add_f32_e32 v21, v25, v21
	v_sub_f32_e32 v24, v24, v20
	v_div_scale_f32 v20, s[0:1], v21, v21, v3
	v_div_scale_f32 v26, s[0:1], v21, v21, v24
	v_rcp_f32_e32 v27, v20
	v_rcp_f32_e32 v28, v26
	v_div_scale_f32 v25, vcc, v3, v21, v3
	v_fma_f32 v30, -v20, v27, 1.0
	v_fma_f32 v31, -v26, v28, 1.0
	v_fmac_f32_e32 v27, v30, v27
	v_div_scale_f32 v29, s[0:1], v24, v21, v24
	v_fmac_f32_e32 v28, v31, v28
	v_mul_f32_e32 v30, v25, v27
	v_mul_f32_e32 v31, v29, v28
	v_fma_f32 v32, -v20, v30, v25
	v_fma_f32 v33, -v26, v31, v29
	v_fmac_f32_e32 v30, v32, v27
	v_fmac_f32_e32 v31, v33, v28
	v_fma_f32 v20, -v20, v30, v25
	v_fma_f32 v25, -v26, v31, v29
	v_div_fmas_f32 v20, v20, v27, v30
	s_mov_b64 vcc, s[0:1]
	v_div_fixup_f32 v20, v20, v21, v3
	v_div_fmas_f32 v3, v25, v28, v31
	v_div_fixup_f32 v24, v3, v21, v24
	s_waitcnt vmcnt(3)
	v_pk_mul_f32 v[26:27], v[4:5], v[24:25] op_sel_hi:[1,0]
	v_pk_mul_f32 v[28:29], v[6:7], v[24:25] op_sel_hi:[1,0]
	s_waitcnt vmcnt(2)
	v_pk_mul_f32 v[30:31], v[8:9], v[24:25] op_sel_hi:[1,0]
	v_pk_mul_f32 v[32:33], v[10:11], v[24:25] op_sel_hi:[1,0]
	s_waitcnt vmcnt(1)
	v_pk_mul_f32 v[34:35], v[12:13], v[24:25] op_sel_hi:[1,0]
	v_pk_mul_f32 v[36:37], v[14:15], v[24:25] op_sel_hi:[1,0]
	s_waitcnt vmcnt(0)
	v_pk_mul_f32 v[38:39], v[16:17], v[24:25] op_sel_hi:[1,0]
	v_pk_mul_f32 v[24:25], v[18:19], v[24:25] op_sel_hi:[1,0]
	v_pk_fma_f32 v[12:13], v[12:13], v[20:21], v[26:27] op_sel_hi:[1,0,1] neg_lo:[0,0,1] neg_hi:[0,0,1]
	v_pk_fma_f32 v[6:7], v[6:7], v[20:21], v[36:37] op_sel_hi:[1,0,1]
	v_pk_fma_f32 v[4:5], v[4:5], v[20:21], v[34:35] op_sel_hi:[1,0,1]
	v_pk_fma_f32 v[10:11], v[10:11], v[20:21], v[24:25] op_sel_hi:[1,0,1]
	v_pk_fma_f32 v[8:9], v[8:9], v[20:21], v[38:39] op_sel_hi:[1,0,1]
	v_cvt_pk_bf16_f32 v116, v12, v13
	v_lshl_add_u64 v[12:13], v[140:141], 0, v[132:133]
	v_pk_fma_f32 v[14:15], v[14:15], v[20:21], v[28:29] op_sel_hi:[1,0,1] neg_lo:[0,0,1] neg_hi:[0,0,1]
	v_pk_fma_f32 v[18:19], v[18:19], v[20:21], v[32:33] op_sel_hi:[1,0,1] neg_lo:[0,0,1] neg_hi:[0,0,1]
	v_pk_fma_f32 v[16:17], v[16:17], v[20:21], v[30:31] op_sel_hi:[1,0,1] neg_lo:[0,0,1] neg_hi:[0,0,1]
	v_cvt_pk_bf16_f32 v117, v14, v15
	s_lshl_b32 s1, s6, 3
	v_cvt_pk_bf16_f32 v118, v16, v17
	v_cvt_pk_bf16_f32 v119, v18, v19
	v_cvt_pk_bf16_f32 v112, v4, v5
	v_cvt_pk_bf16_f32 v113, v6, v7
	v_cvt_pk_bf16_f32 v114, v8, v9
	v_cvt_pk_bf16_f32 v115, v10, v11
	s_and_b32 s15, s1, 0x1800
	v_or_b32_e32 v3, s15, v174
	v_lshlrev_b32_e32 v3, 3, v3
	s_lshl_b32 s0, s6, 4
	v_and_b32_e32 v3, 0xc080, v3
	s_and_b32 s14, s0, 16
	v_or_b32_e32 v3, s16, v3
	v_or_b32_e32 v132, s14, v176
	v_lshl_or_b32 v3, v3, 9, v177
	v_or3_b32 v14, s14, v175, v3
	v_or_b32_e32 v3, v3, v132
	v_lshlrev_b32_e32 v3, 1, v3
	v_lshlrev_b32_e32 v14, 1, v14
	v_or_b32_e32 v15, 16, v3
	v_mul_f32_e32 v0, v0, v1
	v_mul_f32_e32 v1, 0.15915494, v0
	v_cos_f32_e32 v0, v1
	v_sin_f32_e32 v1, v1
	s_mov_b64 s[0:1], 0
	s_mov_b32 s16, 0
	v_pk_mul_f32 v[198:199], v[126:127], v[198:199]
	v_pk_mul_f32 v[196:197], v[124:125], v[196:197]
	v_pk_mul_f32 v[202:203], v[130:131], v[202:203]
	v_pk_mul_f32 v[200:201], v[128:129], v[200:201]
	s_nop 0
	v_cvt_pk_bf16_f32 v64, v196, v200
	v_cvt_pk_bf16_f32 v65, v197, v201
	v_cvt_pk_bf16_f32 v66, v198, v202
	v_cvt_pk_bf16_f32 v67, v199, v203
	v_pk_mul_f32 v[206:207], v[126:127], v[206:207]
	v_pk_mul_f32 v[204:205], v[124:125], v[204:205]
	v_pk_mul_f32 v[210:211], v[130:131], v[210:211]
	v_pk_mul_f32 v[208:209], v[128:129], v[208:209]
	s_nop 0
	v_cvt_pk_bf16_f32 v68, v204, v208
	v_cvt_pk_bf16_f32 v69, v205, v209
	v_cvt_pk_bf16_f32 v70, v206, v210
	v_cvt_pk_bf16_f32 v71, v207, v211
	v_pk_mul_f32 v[214:215], v[126:127], v[214:215]
	v_pk_mul_f32 v[212:213], v[124:125], v[212:213]
	v_pk_mul_f32 v[218:219], v[130:131], v[218:219]
	v_pk_mul_f32 v[216:217], v[128:129], v[216:217]
	s_nop 0
	v_cvt_pk_bf16_f32 v72, v212, v216
	v_cvt_pk_bf16_f32 v73, v213, v217
	v_cvt_pk_bf16_f32 v74, v214, v218
	v_cvt_pk_bf16_f32 v75, v215, v219
	v_pk_mul_f32 v[222:223], v[126:127], v[222:223]
	v_pk_mul_f32 v[220:221], v[124:125], v[220:221]
	v_pk_mul_f32 v[226:227], v[130:131], v[226:227]
	v_pk_mul_f32 v[224:225], v[128:129], v[224:225]
	s_nop 0
	v_cvt_pk_bf16_f32 v76, v220, v224
	v_cvt_pk_bf16_f32 v77, v221, v225
	v_cvt_pk_bf16_f32 v78, v222, v226
	v_cvt_pk_bf16_f32 v79, v223, v227
	v_pk_mul_f32 v[230:231], v[126:127], v[230:231]
	v_pk_mul_f32 v[228:229], v[124:125], v[228:229]
	v_pk_mul_f32 v[234:235], v[130:131], v[234:235]
	v_pk_mul_f32 v[232:233], v[128:129], v[232:233]
	s_nop 0
	v_cvt_pk_bf16_f32 v84, v228, v232
	v_cvt_pk_bf16_f32 v85, v229, v233
	v_cvt_pk_bf16_f32 v86, v230, v234
	v_cvt_pk_bf16_f32 v87, v231, v235
	v_pk_mul_f32 v[238:239], v[126:127], v[238:239]
	v_pk_mul_f32 v[236:237], v[124:125], v[236:237]
	v_pk_mul_f32 v[242:243], v[130:131], v[242:243]
	v_pk_mul_f32 v[240:241], v[128:129], v[240:241]
	s_nop 0
	v_cvt_pk_bf16_f32 v88, v236, v240
	v_cvt_pk_bf16_f32 v89, v237, v241
	v_cvt_pk_bf16_f32 v90, v238, v242
	v_cvt_pk_bf16_f32 v91, v239, v243
	v_pk_mul_f32 v[246:247], v[126:127], v[246:247]
	v_pk_mul_f32 v[244:245], v[124:125], v[244:245]
	v_pk_mul_f32 v[42:43], v[130:131], v[42:43]
	v_pk_mul_f32 v[40:41], v[128:129], v[40:41]
	s_nop 0
	v_cvt_pk_bf16_f32 v96, v244, v40
	v_cvt_pk_bf16_f32 v97, v245, v41
	v_cvt_pk_bf16_f32 v98, v246, v42
	v_cvt_pk_bf16_f32 v99, v247, v43
	v_lshl_add_u64 v[12:13], v[142:143], 0, s[4:5]
	s_bfe_u32 s4, s6, 0x10001
	v_pk_mul_f32 v[46:47], v[126:127], v[46:47]
	v_pk_mul_f32 v[44:45], v[124:125], v[44:45]
	v_pk_mul_f32 v[50:51], v[130:131], v[50:51]
	v_pk_mul_f32 v[48:49], v[128:129], v[48:49]
	s_nop 0
	v_cvt_pk_bf16_f32 v108, v44, v48
	v_cvt_pk_bf16_f32 v109, v45, v49
	v_cvt_pk_bf16_f32 v110, v46, v50
	v_cvt_pk_bf16_f32 v111, v47, v51
	global_load_dwordx4 v[100:103], v[12:13], off
	global_load_dwordx4 v[80:83], v[12:13], off offset:32
	global_load_dwordx4 v[120:123], v14, s[54:55]
	global_load_dwordx2 v[158:159], v3, s[54:55]
	global_load_dwordx2 v[156:157], v15, s[54:55]
	v_or_b32_e32 v3, s2, v174
	v_pk_mul_f32 v[160:161], v[0:1], v[2:3] op_sel_hi:[1,0]
	v_lshrrev_b32_e32 v187, 3, v3
	v_pk_mov_b32 v[162:163], v[160:161], v[160:161] op_sel:[1,0]
	v_mov_b32_e32 v164, v160
	v_mov_b32_e32 v165, v160
	v_mov_b32_e32 v166, v161
	v_mov_b32_e32 v167, v161
	v_mov_b32_e32 v184, 0xbdd2d3e8
	global_load_dwordx4 v[168:171], v[152:153], off
	s_add_u32 s0, s0, 0x40000
	s_addc_u32 s1, s1, 0
	v_lshl_add_u64 v[216:217], v[152:153], 0, s[0:1]
	global_load_dwordx4 v[156:159], v[216:217], off
	s_add_u32 s0, s0, 0x40000
	s_addc_u32 s1, s1, 0
	v_lshl_add_u64 v[216:217], v[152:153], 0, s[0:1]
	global_load_dwordx4 v[178:181], v[216:217], off
.Lscan_tile:
	s_cmp_lt_u32 s16, 0x2800
	s_cbranch_scc1 .Lscan_w3_0
	s_waitcnt vmcnt(11)
	s_branch .Lscan_go_0

.Lscan_go_0:
	v_mfma_f32_32x32x16_bf16 v[0:15], v[120:123], v[104:107], 0
	s_and_b32 s18, s16, 0x2000
	s_and_b32 s17, s2, 0x1f00
	s_or_b32 s17, s17, s13
	s_lshl_b32 s17, s17, 12
	s_and_b32 s17, s17, 0x1ffc000
	s_addk_i32 s16, 0x800
	v_mfma_f32_32x32x16_bf16 v[16:31], v[120:123], v[116:119], 0
	v_add_u32_e32 v222, s2, v174
	v_and_or_b32 v223, v187, 14, s4
	v_lshlrev_b32_e32 v225, 5, v222
	v_lshlrev_b32_e32 v226, 1, v222
	v_lshl_or_b32 v227, v223, 9, s18
	v_and_b32_e32 v222, 0x1e0, v225
	v_mfma_f32_32x32x16_bf16 v[32:47], v[120:123], v[92:95], 0
	v_and_b32_e32 v223, 16, v226
	v_or_b32_e32 v224, v222, v132
	v_bitop3_b32 v222, v222, v223, v132 bitop3:0x36
	v_or_b32_e32 v225, s17, v227
	v_bitop3_b32 v226, v224, v223, 8 bitop3:0x36
	v_or_b32_e32 v227, v222, v225
	v_mfma_f32_32x32x16_bf16 v[196:211], v[120:123], v[112:115], 0
	v_mov_b32_e32 v218, v120
	v_mov_b32_e32 v219, v121
	v_mov_b32_e32 v220, v122
	v_mov_b32_e32 v221, v123
	s_nop 0
	v_permlane32_swap_b32_e32 v218, v220
	v_permlane32_swap_b32_e32 v219, v221
	s_add_u32 s0, s0, 0x40000
	s_addc_u32 s1, s1, 0
	v_lshl_add_u64 v[216:217], v[152:153], 0, s[0:1]
	global_load_dwordx4 v[120:123], v[216:217], off
	v_lshlrev_b32_e32 v228, 16, v218
	v_and_b32_e32 v229, 0xffff0000, v218
	v_lshlrev_b32_e32 v230, 16, v219
	v_and_b32_e32 v231, 0xffff0000, v219
	v_lshlrev_b32_e32 v232, 16, v220
	v_and_b32_e32 v233, 0xffff0000, v220
	v_lshlrev_b32_e32 v251, 16, v221
	v_and_b32_e32 v252, 0xffff0000, v221
	v_or_b32_e32 v254, v226, v225
	v_lshlrev_b32_e32 v253, 1, v227
	v_lshlrev_b32_e32 v254, 1, v254
	v_permlane32_swap_b32_e32 v0, v16
	v_permlane32_swap_b32_e32 v1, v17
	v_permlane32_swap_b32_e32 v2, v18
	v_permlane32_swap_b32_e32 v3, v19
	v_permlane32_swap_b32_e32 v4, v20
	v_permlane32_swap_b32_e32 v5, v21
	v_permlane32_swap_b32_e32 v6, v22
	v_permlane32_swap_b32_e32 v7, v23
	v_permlane32_swap_b32_e32 v8, v24
	v_permlane32_swap_b32_e32 v9, v25
	v_permlane32_swap_b32_e32 v10, v26
	v_permlane32_swap_b32_e32 v11, v27
	v_permlane32_swap_b32_e32 v12, v28
	v_permlane32_swap_b32_e32 v13, v29
	v_permlane32_swap_b32_e32 v14, v30
	v_permlane32_swap_b32_e32 v15, v31
	v_permlane32_swap_b32_e32 v32, v196
	v_permlane32_swap_b32_e32 v33, v197
	v_permlane32_swap_b32_e32 v34, v198
	v_permlane32_swap_b32_e32 v35, v199
	v_permlane32_swap_b32_e32 v36, v200
	v_permlane32_swap_b32_e32 v37, v201
	v_permlane32_swap_b32_e32 v38, v202
	v_permlane32_swap_b32_e32 v39, v203
	v_permlane32_swap_b32_e32 v40, v204
	v_permlane32_swap_b32_e32 v41, v205
	v_permlane32_swap_b32_e32 v42, v206
	v_permlane32_swap_b32_e32 v43, v207
	v_permlane32_swap_b32_e32 v44, v208
	v_permlane32_swap_b32_e32 v45, v209
	v_permlane32_swap_b32_e32 v46, v210
	v_permlane32_swap_b32_e32 v47, v211
	v_fmac_f32_e32 v0, v160, v188
	v_fmac_f32_e32 v32, v160, v189
	v_fma_f32 v0, -v161, v189, v0
	v_fmac_f32_e32 v32, v161, v188
	v_fmac_f32_e32 v1, v160, v0
	v_fmac_f32_e32 v33, v160, v32
	v_cvt_pk_bf16_f32 v212, v0, v32
	v_fma_f32 v1, -v161, v32, v1
	v_fmac_f32_e32 v33, v161, v0
	ds_write_b32 v185, v212 offset:18432
	v_fmac_f32_e32 v2, v160, v1
	v_fmac_f32_e32 v34, v160, v33
	v_cvt_pk_bf16_f32 v213, v1, v33
	v_fma_f32 v2, -v161, v33, v2
	v_fmac_f32_e32 v34, v161, v1
	ds_write_b32 v185, v213 offset:18704
	v_fmac_f32_e32 v3, v160, v2
	v_fmac_f32_e32 v35, v160, v34
	v_cvt_pk_bf16_f32 v214, v2, v34
	v_fma_f32 v3, -v161, v34, v3
	v_fmac_f32_e32 v35, v161, v2
	ds_write_b32 v185, v214 offset:18976
	v_fmac_f32_e32 v16, v160, v3
	v_fmac_f32_e32 v196, v160, v35
	v_cvt_pk_bf16_f32 v215, v3, v35
	v_fma_f32 v16, -v161, v35, v16
	v_fmac_f32_e32 v196, v161, v3
	ds_write_b32 v185, v215 offset:19248
	v_fmac_f32_e32 v17, v160, v16
	v_fmac_f32_e32 v197, v160, v196
	v_cvt_pk_bf16_f32 v212, v16, v196
	v_fma_f32 v17, -v161, v196, v17
	v_fmac_f32_e32 v197, v161, v16
	ds_write_b32 v185, v212 offset:19520
	v_fmac_f32_e32 v18, v160, v17
	v_fmac_f32_e32 v198, v160, v197
	v_cvt_pk_bf16_f32 v213, v17, v197
	v_fma_f32 v18, -v161, v197, v18
	v_fmac_f32_e32 v198, v161, v17
	ds_write_b32 v185, v213 offset:19792
	v_fmac_f32_e32 v19, v160, v18
	v_fmac_f32_e32 v199, v160, v198
	v_cvt_pk_bf16_f32 v214, v18, v198
	v_fma_f32 v19, -v161, v198, v19
	v_fmac_f32_e32 v199, v161, v18
	ds_write_b32 v185, v214 offset:20064
	v_fmac_f32_e32 v4, v160, v19
	v_fmac_f32_e32 v36, v160, v199
	v_cvt_pk_bf16_f32 v215, v19, v199
	v_fma_f32 v4, -v161, v199, v4
	v_fmac_f32_e32 v36, v161, v19
	ds_write_b32 v185, v215 offset:20336
	v_fmac_f32_e32 v5, v160, v4
	v_fmac_f32_e32 v37, v160, v36
	v_cvt_pk_bf16_f32 v212, v4, v36
	v_fma_f32 v5, -v161, v36, v5
	v_fmac_f32_e32 v37, v161, v4
	ds_write_b32 v185, v212 offset:20608
	v_fmac_f32_e32 v6, v160, v5
	v_fmac_f32_e32 v38, v160, v37
	v_cvt_pk_bf16_f32 v213, v5, v37
	v_fma_f32 v6, -v161, v37, v6
	v_fmac_f32_e32 v38, v161, v5
	ds_write_b32 v185, v213 offset:20880
	v_fmac_f32_e32 v7, v160, v6
	v_fmac_f32_e32 v39, v160, v38
	v_cvt_pk_bf16_f32 v214, v6, v38
	v_fma_f32 v7, -v161, v38, v7
	v_fmac_f32_e32 v39, v161, v6
	ds_write_b32 v185, v214 offset:21152
	v_fmac_f32_e32 v20, v160, v7
	v_fmac_f32_e32 v200, v160, v39
	v_cvt_pk_bf16_f32 v215, v7, v39
	v_fma_f32 v20, -v161, v39, v20
	v_fmac_f32_e32 v200, v161, v7
	ds_write_b32 v185, v215 offset:21424
	v_fmac_f32_e32 v21, v160, v20
	v_fmac_f32_e32 v201, v160, v200
	v_cvt_pk_bf16_f32 v212, v20, v200
	v_fma_f32 v21, -v161, v200, v21
	v_fmac_f32_e32 v201, v161, v20
	ds_write_b32 v185, v212 offset:21696
	v_fmac_f32_e32 v22, v160, v21
	v_fmac_f32_e32 v202, v160, v201
	v_cvt_pk_bf16_f32 v213, v21, v201
	v_fma_f32 v22, -v161, v201, v22
	v_fmac_f32_e32 v202, v161, v21
	ds_write_b32 v185, v213 offset:21968
	v_fmac_f32_e32 v23, v160, v22
	v_fmac_f32_e32 v203, v160, v202
	v_cvt_pk_bf16_f32 v214, v22, v202
	v_fma_f32 v23, -v161, v202, v23
	v_fmac_f32_e32 v203, v161, v22
	ds_write_b32 v185, v214 offset:22240
	v_fmac_f32_e32 v8, v160, v23
	v_fmac_f32_e32 v40, v160, v203
	v_cvt_pk_bf16_f32 v215, v23, v203
	v_fma_f32 v8, -v161, v203, v8
	v_fmac_f32_e32 v40, v161, v23
	ds_write_b32 v185, v215 offset:22512
	v_fmac_f32_e32 v9, v160, v8
	v_fmac_f32_e32 v41, v160, v40
	v_cvt_pk_bf16_f32 v212, v8, v40
	v_fma_f32 v9, -v161, v40, v9
	v_fmac_f32_e32 v41, v161, v8
	ds_write_b32 v185, v212 offset:22784
	v_fmac_f32_e32 v10, v160, v9
	v_fmac_f32_e32 v42, v160, v41
	v_cvt_pk_bf16_f32 v213, v9, v41
	v_fma_f32 v10, -v161, v41, v10
	v_fmac_f32_e32 v42, v161, v9
	ds_write_b32 v185, v213 offset:23056
	v_fmac_f32_e32 v11, v160, v10
	v_fmac_f32_e32 v43, v160, v42
	v_cvt_pk_bf16_f32 v214, v10, v42
	v_fma_f32 v11, -v161, v42, v11
	v_fmac_f32_e32 v43, v161, v10
	ds_write_b32 v185, v214 offset:23328
	v_fmac_f32_e32 v24, v160, v11
	v_fmac_f32_e32 v204, v160, v43
	v_cvt_pk_bf16_f32 v215, v11, v43
	v_fma_f32 v24, -v161, v43, v24
	v_fmac_f32_e32 v204, v161, v11
	ds_write_b32 v185, v215 offset:23600
	v_fmac_f32_e32 v25, v160, v24
	v_fmac_f32_e32 v205, v160, v204
	v_cvt_pk_bf16_f32 v212, v24, v204
	v_fma_f32 v25, -v161, v204, v25
	v_fmac_f32_e32 v205, v161, v24
	ds_write_b32 v185, v212 offset:23872
	v_fmac_f32_e32 v26, v160, v25
	v_fmac_f32_e32 v206, v160, v205
	v_cvt_pk_bf16_f32 v213, v25, v205
	v_fma_f32 v26, -v161, v205, v26
	v_fmac_f32_e32 v206, v161, v25
	ds_write_b32 v185, v213 offset:24144
	v_fmac_f32_e32 v27, v160, v26
	v_fmac_f32_e32 v207, v160, v206
	v_cvt_pk_bf16_f32 v214, v26, v206
	v_fma_f32 v27, -v161, v206, v27
	v_fmac_f32_e32 v207, v161, v26
	ds_write_b32 v185, v214 offset:24416
	v_fmac_f32_e32 v12, v160, v27
	v_fmac_f32_e32 v44, v160, v207
	v_cvt_pk_bf16_f32 v215, v27, v207
	v_fma_f32 v12, -v161, v207, v12
	v_fmac_f32_e32 v44, v161, v27
	ds_write_b32 v185, v215 offset:24688
	v_fmac_f32_e32 v13, v160, v12
	v_fmac_f32_e32 v45, v160, v44
	v_cvt_pk_bf16_f32 v212, v12, v44
	v_fma_f32 v13, -v161, v44, v13
	v_fmac_f32_e32 v45, v161, v12
	ds_write_b32 v185, v212 offset:24960
	v_fmac_f32_e32 v14, v160, v13
	v_fmac_f32_e32 v46, v160, v45
	v_cvt_pk_bf16_f32 v213, v13, v45
	v_fma_f32 v14, -v161, v45, v14
	v_fmac_f32_e32 v46, v161, v13
	ds_write_b32 v185, v213 offset:25232
	v_fmac_f32_e32 v15, v160, v14
	v_fmac_f32_e32 v47, v160, v46
	v_cvt_pk_bf16_f32 v214, v14, v46
	v_fma_f32 v15, -v161, v46, v15
	v_fmac_f32_e32 v47, v161, v14
	ds_write_b32 v185, v214 offset:25504
	v_fmac_f32_e32 v28, v160, v15
	v_fmac_f32_e32 v208, v160, v47
	v_cvt_pk_bf16_f32 v215, v15, v47
	v_fma_f32 v28, -v161, v47, v28
	v_fmac_f32_e32 v208, v161, v15
	ds_write_b32 v185, v215 offset:25776
	v_fmac_f32_e32 v29, v160, v28
	v_fmac_f32_e32 v209, v160, v208
	v_cvt_pk_bf16_f32 v212, v28, v208
	v_fma_f32 v29, -v161, v208, v29
	v_fmac_f32_e32 v209, v161, v28
	ds_write_b32 v185, v212 offset:26048
	v_fmac_f32_e32 v30, v160, v29
	v_fmac_f32_e32 v210, v160, v209
	v_cvt_pk_bf16_f32 v213, v29, v209
	v_fma_f32 v30, -v161, v209, v30
	v_fmac_f32_e32 v210, v161, v29
	ds_write_b32 v185, v213 offset:26320
	v_fmac_f32_e32 v31, v160, v30
	v_fmac_f32_e32 v211, v160, v210
	v_cvt_pk_bf16_f32 v214, v30, v210
	v_fma_f32 v31, -v161, v210, v31
	v_fmac_f32_e32 v211, v161, v30
	ds_write_b32 v185, v214 offset:26592
	v_mov_b32_e32 v188, v31
	v_mov_b32_e32 v189, v211
	v_cvt_pk_bf16_f32 v215, v31, v211
	ds_write_b32 v185, v215 offset:26864
	s_waitcnt lgkmcnt(0)
	ds_read_b128 v[32:35], v186 offset:18432
	ds_read_b128 v[36:39], v186 offset:18464
	ds_read_b128 v[40:43], v186 offset:18496
	ds_read_b128 v[44:47], v186 offset:18528
	ds_read_b128 v[196:199], v186 offset:18560
	ds_read_b128 v[200:203], v186 offset:18592
	ds_read_b128 v[204:207], v186 offset:18624
	ds_read_b128 v[208:211], v186 offset:18656
	s_waitcnt lgkmcnt(7)
	v_mfma_f32_32x32x16_bf16 v[48:63], v[64:67], v[32:35], 0
	v_fmac_f32_e32 v234, v100, v162
	v_fmac_f32_e32 v235, v101, v163
	v_fmac_f32_e32 v236, v102, v164
	v_fmac_f32_e32 v237, v103, v165
	v_fmac_f32_e32 v238, v80, v166
	v_fmac_f32_e32 v239, v81, v167
	v_fmac_f32_e32 v240, v82, v192
	v_fmac_f32_e32 v241, v83, v193
	v_mul_f32_e32 v242, v234, v234
	s_waitcnt lgkmcnt(6)
	v_mfma_f32_32x32x16_bf16 v[48:63], v[68:71], v[36:39], v[48:63]
	v_mul_f32_e32 v243, v235, v235
	v_mul_f32_e32 v244, v236, v236
	v_mul_f32_e32 v245, v237, v237
	v_mul_f32_e32 v246, v238, v238
	v_mul_f32_e32 v247, v239, v239
	v_mul_f32_e32 v248, v240, v240
	v_mul_f32_e32 v249, v241, v241
	v_fmaak_f32 v242, v242, v184, 0xc0135761
	v_fmaak_f32 v243, v243, v184, 0xc0135761
	s_waitcnt lgkmcnt(5)
	v_mfma_f32_32x32x16_bf16 v[48:63], v[72:75], v[40:43], v[48:63]
	v_fmaak_f32 v244, v244, v184, 0xc0135761
	v_fmaak_f32 v245, v245, v184, 0xc0135761
	v_fmaak_f32 v246, v246, v184, 0xc0135761
	v_fmaak_f32 v247, v247, v184, 0xc0135761
	v_fmaak_f32 v248, v248, v184, 0xc0135761
	v_fmaak_f32 v249, v249, v184, 0xc0135761
	v_mul_f32_e32 v242, v234, v242
	v_mul_f32_e32 v243, v235, v243
	v_mul_f32_e32 v244, v236, v244
	s_waitcnt lgkmcnt(4)
	v_mfma_f32_32x32x16_bf16 v[48:63], v[76:79], v[44:47], v[48:63]
	v_mul_f32_e32 v245, v237, v245
	v_mul_f32_e32 v246, v238, v246
	v_mul_f32_e32 v247, v239, v247
	v_mul_f32_e32 v248, v240, v248
	v_mul_f32_e32 v249, v241, v249
	v_exp_f32_e32 v242, v242
	v_exp_f32_e32 v243, v243
	v_exp_f32_e32 v244, v244
	v_exp_f32_e32 v245, v245
	s_waitcnt lgkmcnt(3)
	v_mfma_f32_32x32x16_bf16 v[48:63], v[84:87], v[196:199], v[48:63]
	v_exp_f32_e32 v246, v246
	v_exp_f32_e32 v247, v247
	v_exp_f32_e32 v248, v248
	v_exp_f32_e32 v249, v249
	v_add_f32_e32 v242, 1.0, v242
	v_add_f32_e32 v243, 1.0, v243
	v_add_f32_e32 v244, 1.0, v244
	v_add_f32_e32 v245, 1.0, v245
	s_waitcnt lgkmcnt(2)
	v_mfma_f32_32x32x16_bf16 v[48:63], v[88:91], v[200:203], v[48:63]
	v_add_f32_e32 v246, 1.0, v246
	v_add_f32_e32 v247, 1.0, v247
	v_add_f32_e32 v248, 1.0, v248
	v_add_f32_e32 v249, 1.0, v249
	v_rcp_f32_e32 v242, v242
	v_rcp_f32_e32 v243, v243
	v_rcp_f32_e32 v244, v244
	v_rcp_f32_e32 v245, v245
	s_waitcnt lgkmcnt(1)
	v_mfma_f32_32x32x16_bf16 v[48:63], v[96:99], v[204:207], v[48:63]
	v_rcp_f32_e32 v246, v246
	v_rcp_f32_e32 v247, v247
	v_rcp_f32_e32 v248, v248
	v_rcp_f32_e32 v249, v249
	v_mul_f32_e32 v234, v234, v242
	v_mul_f32_e32 v235, v235, v243
	v_mul_f32_e32 v236, v236, v244
	v_mul_f32_e32 v237, v237, v245
	s_waitcnt lgkmcnt(0)
	v_mfma_f32_32x32x16_bf16 v[48:63], v[108:111], v[208:211], v[48:63]
	v_mul_f32_e32 v238, v238, v246
	v_mul_f32_e32 v239, v239, v247
	v_mul_f32_e32 v240, v240, v248
	v_mul_f32_e32 v241, v241, v249
	v_cvt_pk_bf16_f32 v242, v234, v235
	v_cvt_pk_bf16_f32 v243, v236, v237
	v_cvt_pk_bf16_f32 v244, v238, v239
	v_cvt_pk_bf16_f32 v245, v240, v241
	s_cmp_eq_u32 s16, 0x800
	s_cbranch_scc1 .Lscan_nostore
	global_store_dwordx2 v190, v[242:243], s[90:91]
	global_store_dwordx2 v191, v[244:245], s[90:91]
.Lscan_nostore:
	s_add_i32 s2, s2, 32
	v_add_u32_e32 v187, 4, v187
	s_cmp_lt_u32 s16, 0x2800
	s_cbranch_scc1 .Lscan_w3_1
	s_waitcnt vmcnt(11)
	s_branch .Lscan_go_1

.Lscan_go_1:
	v_mfma_f32_32x32x16_bf16 v[0:15], v[168:171], v[104:107], 0
	s_and_b32 s18, s16, 0x2000
	s_and_b32 s17, s2, 0x1f00
	s_or_b32 s17, s17, s13
	s_lshl_b32 s17, s17, 12
	s_and_b32 s17, s17, 0x1ffc000
	s_addk_i32 s16, 0x800
	v_mfma_f32_32x32x16_bf16 v[16:31], v[168:171], v[116:119], 0
	v_add_u32_e32 v222, s2, v174
	v_and_or_b32 v223, v187, 14, s4
	v_lshlrev_b32_e32 v225, 5, v222
	v_lshlrev_b32_e32 v226, 1, v222
	v_lshl_or_b32 v227, v223, 9, s18
	v_and_b32_e32 v222, 0x1e0, v225
	v_mfma_f32_32x32x16_bf16 v[32:47], v[168:171], v[92:95], 0
	v_and_b32_e32 v223, 16, v226
	v_or_b32_e32 v224, v222, v132
	v_bitop3_b32 v222, v222, v223, v132 bitop3:0x36
	v_or_b32_e32 v225, s17, v227
	v_bitop3_b32 v226, v224, v223, 8 bitop3:0x36
	v_or_b32_e32 v227, v222, v225
	v_mfma_f32_32x32x16_bf16 v[196:211], v[168:171], v[112:115], 0
	v_mov_b32_e32 v218, v168
	v_mov_b32_e32 v219, v169
	v_mov_b32_e32 v220, v170
	v_mov_b32_e32 v221, v171
	s_nop 0
	v_permlane32_swap_b32_e32 v218, v220
	v_permlane32_swap_b32_e32 v219, v221
	s_add_u32 s0, s0, 0x40000
	s_addc_u32 s1, s1, 0
	v_lshl_add_u64 v[216:217], v[152:153], 0, s[0:1]
	global_load_dwordx4 v[168:171], v[216:217], off
	v_lshlrev_b32_e32 v162, 16, v218
	v_and_b32_e32 v163, 0xffff0000, v218
	v_lshlrev_b32_e32 v164, 16, v219
	v_and_b32_e32 v165, 0xffff0000, v219
	v_lshlrev_b32_e32 v166, 16, v220
	v_and_b32_e32 v167, 0xffff0000, v220
	v_lshlrev_b32_e32 v192, 16, v221
	v_and_b32_e32 v193, 0xffff0000, v221
	v_or_b32_e32 v191, v226, v225
	v_lshlrev_b32_e32 v190, 1, v227
	v_lshlrev_b32_e32 v191, 1, v191
	v_permlane32_swap_b32_e32 v0, v16
	v_permlane32_swap_b32_e32 v1, v17
	v_permlane32_swap_b32_e32 v2, v18
	v_permlane32_swap_b32_e32 v3, v19
	v_permlane32_swap_b32_e32 v4, v20
	v_permlane32_swap_b32_e32 v5, v21
	v_permlane32_swap_b32_e32 v6, v22
	v_permlane32_swap_b32_e32 v7, v23
	v_permlane32_swap_b32_e32 v8, v24
	v_permlane32_swap_b32_e32 v9, v25
	v_permlane32_swap_b32_e32 v10, v26
	v_permlane32_swap_b32_e32 v11, v27
	v_permlane32_swap_b32_e32 v12, v28
	v_permlane32_swap_b32_e32 v13, v29
	v_permlane32_swap_b32_e32 v14, v30
	v_permlane32_swap_b32_e32 v15, v31
	v_permlane32_swap_b32_e32 v32, v196
	v_permlane32_swap_b32_e32 v33, v197
	v_permlane32_swap_b32_e32 v34, v198
	v_permlane32_swap_b32_e32 v35, v199
	v_permlane32_swap_b32_e32 v36, v200
	v_permlane32_swap_b32_e32 v37, v201
	v_permlane32_swap_b32_e32 v38, v202
	v_permlane32_swap_b32_e32 v39, v203
	v_permlane32_swap_b32_e32 v40, v204
	v_permlane32_swap_b32_e32 v41, v205
	v_permlane32_swap_b32_e32 v42, v206
	v_permlane32_swap_b32_e32 v43, v207
	v_permlane32_swap_b32_e32 v44, v208
	v_permlane32_swap_b32_e32 v45, v209
	v_permlane32_swap_b32_e32 v46, v210
	v_permlane32_swap_b32_e32 v47, v211
	v_fmac_f32_e32 v0, v160, v188
	v_fmac_f32_e32 v32, v160, v189
	v_fma_f32 v0, -v161, v189, v0
	v_fmac_f32_e32 v32, v161, v188
	v_fmac_f32_e32 v1, v160, v0
	v_fmac_f32_e32 v33, v160, v32
	v_cvt_pk_bf16_f32 v212, v0, v32
	v_fma_f32 v1, -v161, v32, v1
	v_fmac_f32_e32 v33, v161, v0
	ds_write_b32 v185, v212 offset:18432
	v_fmac_f32_e32 v2, v160, v1
	v_fmac_f32_e32 v34, v160, v33
	v_cvt_pk_bf16_f32 v213, v1, v33
	v_fma_f32 v2, -v161, v33, v2
	v_fmac_f32_e32 v34, v161, v1
	ds_write_b32 v185, v213 offset:18704
	v_fmac_f32_e32 v3, v160, v2
	v_fmac_f32_e32 v35, v160, v34
	v_cvt_pk_bf16_f32 v214, v2, v34
	v_fma_f32 v3, -v161, v34, v3
	v_fmac_f32_e32 v35, v161, v2
	ds_write_b32 v185, v214 offset:18976
	v_fmac_f32_e32 v16, v160, v3
	v_fmac_f32_e32 v196, v160, v35
	v_cvt_pk_bf16_f32 v215, v3, v35
	v_fma_f32 v16, -v161, v35, v16
	v_fmac_f32_e32 v196, v161, v3
	ds_write_b32 v185, v215 offset:19248
	v_fmac_f32_e32 v17, v160, v16
	v_fmac_f32_e32 v197, v160, v196
	v_cvt_pk_bf16_f32 v212, v16, v196
	v_fma_f32 v17, -v161, v196, v17
	v_fmac_f32_e32 v197, v161, v16
	ds_write_b32 v185, v212 offset:19520
	v_fmac_f32_e32 v18, v160, v17
	v_fmac_f32_e32 v198, v160, v197
	v_cvt_pk_bf16_f32 v213, v17, v197
	v_fma_f32 v18, -v161, v197, v18
	v_fmac_f32_e32 v198, v161, v17
	ds_write_b32 v185, v213 offset:19792
	v_fmac_f32_e32 v19, v160, v18
	v_fmac_f32_e32 v199, v160, v198
	v_cvt_pk_bf16_f32 v214, v18, v198
	v_fma_f32 v19, -v161, v198, v19
	v_fmac_f32_e32 v199, v161, v18
	ds_write_b32 v185, v214 offset:20064
	v_fmac_f32_e32 v4, v160, v19
	v_fmac_f32_e32 v36, v160, v199
	v_cvt_pk_bf16_f32 v215, v19, v199
	v_fma_f32 v4, -v161, v199, v4
	v_fmac_f32_e32 v36, v161, v19
	ds_write_b32 v185, v215 offset:20336
	v_fmac_f32_e32 v5, v160, v4
	v_fmac_f32_e32 v37, v160, v36
	v_cvt_pk_bf16_f32 v212, v4, v36
	v_fma_f32 v5, -v161, v36, v5
	v_fmac_f32_e32 v37, v161, v4
	ds_write_b32 v185, v212 offset:20608
	v_fmac_f32_e32 v6, v160, v5
	v_fmac_f32_e32 v38, v160, v37
	v_cvt_pk_bf16_f32 v213, v5, v37
	v_fma_f32 v6, -v161, v37, v6
	v_fmac_f32_e32 v38, v161, v5
	ds_write_b32 v185, v213 offset:20880
	v_fmac_f32_e32 v7, v160, v6
	v_fmac_f32_e32 v39, v160, v38
	v_cvt_pk_bf16_f32 v214, v6, v38
	v_fma_f32 v7, -v161, v38, v7
	v_fmac_f32_e32 v39, v161, v6
	ds_write_b32 v185, v214 offset:21152
	v_fmac_f32_e32 v20, v160, v7
	v_fmac_f32_e32 v200, v160, v39
	v_cvt_pk_bf16_f32 v215, v7, v39
	v_fma_f32 v20, -v161, v39, v20
	v_fmac_f32_e32 v200, v161, v7
	ds_write_b32 v185, v215 offset:21424
	v_fmac_f32_e32 v21, v160, v20
	v_fmac_f32_e32 v201, v160, v200
	v_cvt_pk_bf16_f32 v212, v20, v200
	v_fma_f32 v21, -v161, v200, v21
	v_fmac_f32_e32 v201, v161, v20
	ds_write_b32 v185, v212 offset:21696
	v_fmac_f32_e32 v22, v160, v21
	v_fmac_f32_e32 v202, v160, v201
	v_cvt_pk_bf16_f32 v213, v21, v201
	v_fma_f32 v22, -v161, v201, v22
	v_fmac_f32_e32 v202, v161, v21
	ds_write_b32 v185, v213 offset:21968
	v_fmac_f32_e32 v23, v160, v22
	v_fmac_f32_e32 v203, v160, v202
	v_cvt_pk_bf16_f32 v214, v22, v202
	v_fma_f32 v23, -v161, v202, v23
	v_fmac_f32_e32 v203, v161, v22
	ds_write_b32 v185, v214 offset:22240
	v_fmac_f32_e32 v8, v160, v23
	v_fmac_f32_e32 v40, v160, v203
	v_cvt_pk_bf16_f32 v215, v23, v203
	v_fma_f32 v8, -v161, v203, v8
	v_fmac_f32_e32 v40, v161, v23
	ds_write_b32 v185, v215 offset:22512
	v_fmac_f32_e32 v9, v160, v8
	v_fmac_f32_e32 v41, v160, v40
	v_cvt_pk_bf16_f32 v212, v8, v40
	v_fma_f32 v9, -v161, v40, v9
	v_fmac_f32_e32 v41, v161, v8
	ds_write_b32 v185, v212 offset:22784
	v_fmac_f32_e32 v10, v160, v9
	v_fmac_f32_e32 v42, v160, v41
	v_cvt_pk_bf16_f32 v213, v9, v41
	v_fma_f32 v10, -v161, v41, v10
	v_fmac_f32_e32 v42, v161, v9
	ds_write_b32 v185, v213 offset:23056
	v_fmac_f32_e32 v11, v160, v10
	v_fmac_f32_e32 v43, v160, v42
	v_cvt_pk_bf16_f32 v214, v10, v42
	v_fma_f32 v11, -v161, v42, v11
	v_fmac_f32_e32 v43, v161, v10
	ds_write_b32 v185, v214 offset:23328
	v_fmac_f32_e32 v24, v160, v11
	v_fmac_f32_e32 v204, v160, v43
	v_cvt_pk_bf16_f32 v215, v11, v43
	v_fma_f32 v24, -v161, v43, v24
	v_fmac_f32_e32 v204, v161, v11
	ds_write_b32 v185, v215 offset:23600
	v_fmac_f32_e32 v25, v160, v24
	v_fmac_f32_e32 v205, v160, v204
	v_cvt_pk_bf16_f32 v212, v24, v204
	v_fma_f32 v25, -v161, v204, v25
	v_fmac_f32_e32 v205, v161, v24
	ds_write_b32 v185, v212 offset:23872
	v_fmac_f32_e32 v26, v160, v25
	v_fmac_f32_e32 v206, v160, v205
	v_cvt_pk_bf16_f32 v213, v25, v205
	v_fma_f32 v26, -v161, v205, v26
	v_fmac_f32_e32 v206, v161, v25
	ds_write_b32 v185, v213 offset:24144
	v_fmac_f32_e32 v27, v160, v26
	v_fmac_f32_e32 v207, v160, v206
	v_cvt_pk_bf16_f32 v214, v26, v206
	v_fma_f32 v27, -v161, v206, v27
	v_fmac_f32_e32 v207, v161, v26
	ds_write_b32 v185, v214 offset:24416
	v_fmac_f32_e32 v12, v160, v27
	v_fmac_f32_e32 v44, v160, v207
	v_cvt_pk_bf16_f32 v215, v27, v207
	v_fma_f32 v12, -v161, v207, v12
	v_fmac_f32_e32 v44, v161, v27
	ds_write_b32 v185, v215 offset:24688
	v_fmac_f32_e32 v13, v160, v12
	v_fmac_f32_e32 v45, v160, v44
	v_cvt_pk_bf16_f32 v212, v12, v44
	v_fma_f32 v13, -v161, v44, v13
	v_fmac_f32_e32 v45, v161, v12
	ds_write_b32 v185, v212 offset:24960
	v_fmac_f32_e32 v14, v160, v13
	v_fmac_f32_e32 v46, v160, v45
	v_cvt_pk_bf16_f32 v213, v13, v45
	v_fma_f32 v14, -v161, v45, v14
	v_fmac_f32_e32 v46, v161, v13
	ds_write_b32 v185, v213 offset:25232
	v_fmac_f32_e32 v15, v160, v14
	v_fmac_f32_e32 v47, v160, v46
	v_cvt_pk_bf16_f32 v214, v14, v46
	v_fma_f32 v15, -v161, v46, v15
	v_fmac_f32_e32 v47, v161, v14
	ds_write_b32 v185, v214 offset:25504
	v_fmac_f32_e32 v28, v160, v15
	v_fmac_f32_e32 v208, v160, v47
	v_cvt_pk_bf16_f32 v215, v15, v47
	v_fma_f32 v28, -v161, v47, v28
	v_fmac_f32_e32 v208, v161, v15
	ds_write_b32 v185, v215 offset:25776
	v_fmac_f32_e32 v29, v160, v28
	v_fmac_f32_e32 v209, v160, v208
	v_cvt_pk_bf16_f32 v212, v28, v208
	v_fma_f32 v29, -v161, v208, v29
	v_fmac_f32_e32 v209, v161, v28
	ds_write_b32 v185, v212 offset:26048
	v_fmac_f32_e32 v30, v160, v29
	v_fmac_f32_e32 v210, v160, v209
	v_cvt_pk_bf16_f32 v213, v29, v209
	v_fma_f32 v30, -v161, v209, v30
	v_fmac_f32_e32 v210, v161, v29
	ds_write_b32 v185, v213 offset:26320
	v_fmac_f32_e32 v31, v160, v30
	v_fmac_f32_e32 v211, v160, v210
	v_cvt_pk_bf16_f32 v214, v30, v210
	v_fma_f32 v31, -v161, v210, v31
	v_fmac_f32_e32 v211, v161, v30
	ds_write_b32 v185, v214 offset:26592
	v_mov_b32_e32 v188, v31
	v_mov_b32_e32 v189, v211
	v_cvt_pk_bf16_f32 v215, v31, v211
	ds_write_b32 v185, v215 offset:26864
	s_waitcnt lgkmcnt(0)
	ds_read_b128 v[32:35], v186 offset:18432
	ds_read_b128 v[36:39], v186 offset:18464
	ds_read_b128 v[40:43], v186 offset:18496
	ds_read_b128 v[44:47], v186 offset:18528
	ds_read_b128 v[196:199], v186 offset:18560
	ds_read_b128 v[200:203], v186 offset:18592
	ds_read_b128 v[204:207], v186 offset:18624
	ds_read_b128 v[208:211], v186 offset:18656
	s_waitcnt lgkmcnt(7)
	v_mfma_f32_32x32x16_bf16 v[234:249], v[64:67], v[32:35], 0
	v_fmac_f32_e32 v48, v100, v228
	v_fmac_f32_e32 v49, v101, v229
	v_fmac_f32_e32 v50, v102, v230
	v_fmac_f32_e32 v51, v103, v231
	v_fmac_f32_e32 v52, v80, v232
	v_fmac_f32_e32 v53, v81, v233
	v_fmac_f32_e32 v54, v82, v251
	v_fmac_f32_e32 v55, v83, v252
	v_mul_f32_e32 v56, v48, v48
	s_waitcnt lgkmcnt(6)
	v_mfma_f32_32x32x16_bf16 v[234:249], v[68:71], v[36:39], v[234:249]
	v_mul_f32_e32 v57, v49, v49
	v_mul_f32_e32 v58, v50, v50
	v_mul_f32_e32 v59, v51, v51
	v_mul_f32_e32 v60, v52, v52
	v_mul_f32_e32 v61, v53, v53
	v_mul_f32_e32 v62, v54, v54
	v_mul_f32_e32 v63, v55, v55
	v_fmaak_f32 v56, v56, v184, 0xc0135761
	v_fmaak_f32 v57, v57, v184, 0xc0135761
	s_waitcnt lgkmcnt(5)
	v_mfma_f32_32x32x16_bf16 v[234:249], v[72:75], v[40:43], v[234:249]
	v_fmaak_f32 v58, v58, v184, 0xc0135761
	v_fmaak_f32 v59, v59, v184, 0xc0135761
	v_fmaak_f32 v60, v60, v184, 0xc0135761
	v_fmaak_f32 v61, v61, v184, 0xc0135761
	v_fmaak_f32 v62, v62, v184, 0xc0135761
	v_fmaak_f32 v63, v63, v184, 0xc0135761
	v_mul_f32_e32 v56, v48, v56
	v_mul_f32_e32 v57, v49, v57
	v_mul_f32_e32 v58, v50, v58
	s_waitcnt lgkmcnt(4)
	v_mfma_f32_32x32x16_bf16 v[234:249], v[76:79], v[44:47], v[234:249]
	v_mul_f32_e32 v59, v51, v59
	v_mul_f32_e32 v60, v52, v60
	v_mul_f32_e32 v61, v53, v61
	v_mul_f32_e32 v62, v54, v62
	v_mul_f32_e32 v63, v55, v63
	v_exp_f32_e32 v56, v56
	v_exp_f32_e32 v57, v57
	v_exp_f32_e32 v58, v58
	v_exp_f32_e32 v59, v59
	s_waitcnt lgkmcnt(3)
	v_mfma_f32_32x32x16_bf16 v[234:249], v[84:87], v[196:199], v[234:249]
	v_exp_f32_e32 v60, v60
	v_exp_f32_e32 v61, v61
	v_exp_f32_e32 v62, v62
	v_exp_f32_e32 v63, v63
	v_add_f32_e32 v56, 1.0, v56
	v_add_f32_e32 v57, 1.0, v57
	v_add_f32_e32 v58, 1.0, v58
	v_add_f32_e32 v59, 1.0, v59
	s_waitcnt lgkmcnt(2)
	v_mfma_f32_32x32x16_bf16 v[234:249], v[88:91], v[200:203], v[234:249]
	v_add_f32_e32 v60, 1.0, v60
	v_add_f32_e32 v61, 1.0, v61
	v_add_f32_e32 v62, 1.0, v62
	v_add_f32_e32 v63, 1.0, v63
	v_rcp_f32_e32 v56, v56
	v_rcp_f32_e32 v57, v57
	v_rcp_f32_e32 v58, v58
	v_rcp_f32_e32 v59, v59
	s_waitcnt lgkmcnt(1)
	v_mfma_f32_32x32x16_bf16 v[234:249], v[96:99], v[204:207], v[234:249]
	v_rcp_f32_e32 v60, v60
	v_rcp_f32_e32 v61, v61
	v_rcp_f32_e32 v62, v62
	v_rcp_f32_e32 v63, v63
	v_mul_f32_e32 v48, v48, v56
	v_mul_f32_e32 v49, v49, v57
	v_mul_f32_e32 v50, v50, v58
	v_mul_f32_e32 v51, v51, v59
	s_waitcnt lgkmcnt(0)
	v_mfma_f32_32x32x16_bf16 v[234:249], v[108:111], v[208:211], v[234:249]
	v_mul_f32_e32 v52, v52, v60
	v_mul_f32_e32 v53, v53, v61
	v_mul_f32_e32 v54, v54, v62
	v_mul_f32_e32 v55, v55, v63
	v_cvt_pk_bf16_f32 v56, v48, v49
	v_cvt_pk_bf16_f32 v57, v50, v51
	v_cvt_pk_bf16_f32 v58, v52, v53
	v_cvt_pk_bf16_f32 v59, v54, v55
	global_store_dwordx2 v253, v[56:57], s[90:91]
	global_store_dwordx2 v254, v[58:59], s[90:91]
	s_add_i32 s2, s2, 32
	v_add_u32_e32 v187, 4, v187
	s_cmp_lt_u32 s16, 0x2800
	s_cbranch_scc1 .Lscan_w3_2
	s_waitcnt vmcnt(11)
	s_branch .Lscan_go_2

.Lscan_go_2:
	v_mfma_f32_32x32x16_bf16 v[0:15], v[156:159], v[104:107], 0
	s_and_b32 s18, s16, 0x2000
	s_and_b32 s17, s2, 0x1f00
	s_or_b32 s17, s17, s13
	s_lshl_b32 s17, s17, 12
	s_and_b32 s17, s17, 0x1ffc000
	s_addk_i32 s16, 0x800
	v_mfma_f32_32x32x16_bf16 v[16:31], v[156:159], v[116:119], 0
	v_add_u32_e32 v222, s2, v174
	v_and_or_b32 v223, v187, 14, s4
	v_lshlrev_b32_e32 v225, 5, v222
	v_lshlrev_b32_e32 v226, 1, v222
	v_lshl_or_b32 v227, v223, 9, s18
	v_and_b32_e32 v222, 0x1e0, v225
	v_mfma_f32_32x32x16_bf16 v[32:47], v[156:159], v[92:95], 0
	v_and_b32_e32 v223, 16, v226
	v_or_b32_e32 v224, v222, v132
	v_bitop3_b32 v222, v222, v223, v132 bitop3:0x36
	v_or_b32_e32 v225, s17, v227
	v_bitop3_b32 v226, v224, v223, 8 bitop3:0x36
	v_or_b32_e32 v227, v222, v225
	v_mfma_f32_32x32x16_bf16 v[196:211], v[156:159], v[112:115], 0
	v_mov_b32_e32 v218, v156
	v_mov_b32_e32 v219, v157
	v_mov_b32_e32 v220, v158
	v_mov_b32_e32 v221, v159
	s_nop 0
	v_permlane32_swap_b32_e32 v218, v220
	v_permlane32_swap_b32_e32 v219, v221
	s_add_u32 s0, s0, 0x40000
	s_addc_u32 s1, s1, 0
	v_lshl_add_u64 v[216:217], v[152:153], 0, s[0:1]
	global_load_dwordx4 v[156:159], v[216:217], off
	v_lshlrev_b32_e32 v228, 16, v218
	v_and_b32_e32 v229, 0xffff0000, v218
	v_lshlrev_b32_e32 v230, 16, v219
	v_and_b32_e32 v231, 0xffff0000, v219
	v_lshlrev_b32_e32 v232, 16, v220
	v_and_b32_e32 v233, 0xffff0000, v220
	v_lshlrev_b32_e32 v251, 16, v221
	v_and_b32_e32 v252, 0xffff0000, v221
	v_or_b32_e32 v254, v226, v225
	v_lshlrev_b32_e32 v253, 1, v227
	v_lshlrev_b32_e32 v254, 1, v254
	v_permlane32_swap_b32_e32 v0, v16
	v_permlane32_swap_b32_e32 v1, v17
	v_permlane32_swap_b32_e32 v2, v18
	v_permlane32_swap_b32_e32 v3, v19
	v_permlane32_swap_b32_e32 v4, v20
	v_permlane32_swap_b32_e32 v5, v21
	v_permlane32_swap_b32_e32 v6, v22
	v_permlane32_swap_b32_e32 v7, v23
	v_permlane32_swap_b32_e32 v8, v24
	v_permlane32_swap_b32_e32 v9, v25
	v_permlane32_swap_b32_e32 v10, v26
	v_permlane32_swap_b32_e32 v11, v27
	v_permlane32_swap_b32_e32 v12, v28
	v_permlane32_swap_b32_e32 v13, v29
	v_permlane32_swap_b32_e32 v14, v30
	v_permlane32_swap_b32_e32 v15, v31
	v_permlane32_swap_b32_e32 v32, v196
	v_permlane32_swap_b32_e32 v33, v197
	v_permlane32_swap_b32_e32 v34, v198
	v_permlane32_swap_b32_e32 v35, v199
	v_permlane32_swap_b32_e32 v36, v200
	v_permlane32_swap_b32_e32 v37, v201
	v_permlane32_swap_b32_e32 v38, v202
	v_permlane32_swap_b32_e32 v39, v203
	v_permlane32_swap_b32_e32 v40, v204
	v_permlane32_swap_b32_e32 v41, v205
	v_permlane32_swap_b32_e32 v42, v206
	v_permlane32_swap_b32_e32 v43, v207
	v_permlane32_swap_b32_e32 v44, v208
	v_permlane32_swap_b32_e32 v45, v209
	v_permlane32_swap_b32_e32 v46, v210
	v_permlane32_swap_b32_e32 v47, v211
	v_fmac_f32_e32 v0, v160, v188
	v_fmac_f32_e32 v32, v160, v189
	v_fma_f32 v0, -v161, v189, v0
	v_fmac_f32_e32 v32, v161, v188
	v_fmac_f32_e32 v1, v160, v0
	v_fmac_f32_e32 v33, v160, v32
	v_cvt_pk_bf16_f32 v212, v0, v32
	v_fma_f32 v1, -v161, v32, v1
	v_fmac_f32_e32 v33, v161, v0
	ds_write_b32 v185, v212 offset:18432
	v_fmac_f32_e32 v2, v160, v1
	v_fmac_f32_e32 v34, v160, v33
	v_cvt_pk_bf16_f32 v213, v1, v33
	v_fma_f32 v2, -v161, v33, v2
	v_fmac_f32_e32 v34, v161, v1
	ds_write_b32 v185, v213 offset:18704
	v_fmac_f32_e32 v3, v160, v2
	v_fmac_f32_e32 v35, v160, v34
	v_cvt_pk_bf16_f32 v214, v2, v34
	v_fma_f32 v3, -v161, v34, v3
	v_fmac_f32_e32 v35, v161, v2
	ds_write_b32 v185, v214 offset:18976
	v_fmac_f32_e32 v16, v160, v3
	v_fmac_f32_e32 v196, v160, v35
	v_cvt_pk_bf16_f32 v215, v3, v35
	v_fma_f32 v16, -v161, v35, v16
	v_fmac_f32_e32 v196, v161, v3
	ds_write_b32 v185, v215 offset:19248
	v_fmac_f32_e32 v17, v160, v16
	v_fmac_f32_e32 v197, v160, v196
	v_cvt_pk_bf16_f32 v212, v16, v196
	v_fma_f32 v17, -v161, v196, v17
	v_fmac_f32_e32 v197, v161, v16
	ds_write_b32 v185, v212 offset:19520
	v_fmac_f32_e32 v18, v160, v17
	v_fmac_f32_e32 v198, v160, v197
	v_cvt_pk_bf16_f32 v213, v17, v197
	v_fma_f32 v18, -v161, v197, v18
	v_fmac_f32_e32 v198, v161, v17
	ds_write_b32 v185, v213 offset:19792
	v_fmac_f32_e32 v19, v160, v18
	v_fmac_f32_e32 v199, v160, v198
	v_cvt_pk_bf16_f32 v214, v18, v198
	v_fma_f32 v19, -v161, v198, v19
	v_fmac_f32_e32 v199, v161, v18
	ds_write_b32 v185, v214 offset:20064
	v_fmac_f32_e32 v4, v160, v19
	v_fmac_f32_e32 v36, v160, v199
	v_cvt_pk_bf16_f32 v215, v19, v199
	v_fma_f32 v4, -v161, v199, v4
	v_fmac_f32_e32 v36, v161, v19
	ds_write_b32 v185, v215 offset:20336
	v_fmac_f32_e32 v5, v160, v4
	v_fmac_f32_e32 v37, v160, v36
	v_cvt_pk_bf16_f32 v212, v4, v36
	v_fma_f32 v5, -v161, v36, v5
	v_fmac_f32_e32 v37, v161, v4
	ds_write_b32 v185, v212 offset:20608
	v_fmac_f32_e32 v6, v160, v5
	v_fmac_f32_e32 v38, v160, v37
	v_cvt_pk_bf16_f32 v213, v5, v37
	v_fma_f32 v6, -v161, v37, v6
	v_fmac_f32_e32 v38, v161, v5
	ds_write_b32 v185, v213 offset:20880
	v_fmac_f32_e32 v7, v160, v6
	v_fmac_f32_e32 v39, v160, v38
	v_cvt_pk_bf16_f32 v214, v6, v38
	v_fma_f32 v7, -v161, v38, v7
	v_fmac_f32_e32 v39, v161, v6
	ds_write_b32 v185, v214 offset:21152
	v_fmac_f32_e32 v20, v160, v7
	v_fmac_f32_e32 v200, v160, v39
	v_cvt_pk_bf16_f32 v215, v7, v39
	v_fma_f32 v20, -v161, v39, v20
	v_fmac_f32_e32 v200, v161, v7
	ds_write_b32 v185, v215 offset:21424
	v_fmac_f32_e32 v21, v160, v20
	v_fmac_f32_e32 v201, v160, v200
	v_cvt_pk_bf16_f32 v212, v20, v200
	v_fma_f32 v21, -v161, v200, v21
	v_fmac_f32_e32 v201, v161, v20
	ds_write_b32 v185, v212 offset:21696
	v_fmac_f32_e32 v22, v160, v21
	v_fmac_f32_e32 v202, v160, v201
	v_cvt_pk_bf16_f32 v213, v21, v201
	v_fma_f32 v22, -v161, v201, v22
	v_fmac_f32_e32 v202, v161, v21
	ds_write_b32 v185, v213 offset:21968
	v_fmac_f32_e32 v23, v160, v22
	v_fmac_f32_e32 v203, v160, v202
	v_cvt_pk_bf16_f32 v214, v22, v202
	v_fma_f32 v23, -v161, v202, v23
	v_fmac_f32_e32 v203, v161, v22
	ds_write_b32 v185, v214 offset:22240
	v_fmac_f32_e32 v8, v160, v23
	v_fmac_f32_e32 v40, v160, v203
	v_cvt_pk_bf16_f32 v215, v23, v203
	v_fma_f32 v8, -v161, v203, v8
	v_fmac_f32_e32 v40, v161, v23
	ds_write_b32 v185, v215 offset:22512
	v_fmac_f32_e32 v9, v160, v8
	v_fmac_f32_e32 v41, v160, v40
	v_cvt_pk_bf16_f32 v212, v8, v40
	v_fma_f32 v9, -v161, v40, v9
	v_fmac_f32_e32 v41, v161, v8
	ds_write_b32 v185, v212 offset:22784
	v_fmac_f32_e32 v10, v160, v9
	v_fmac_f32_e32 v42, v160, v41
	v_cvt_pk_bf16_f32 v213, v9, v41
	v_fma_f32 v10, -v161, v41, v10
	v_fmac_f32_e32 v42, v161, v9
	ds_write_b32 v185, v213 offset:23056
	v_fmac_f32_e32 v11, v160, v10
	v_fmac_f32_e32 v43, v160, v42
	v_cvt_pk_bf16_f32 v214, v10, v42
	v_fma_f32 v11, -v161, v42, v11
	v_fmac_f32_e32 v43, v161, v10
	ds_write_b32 v185, v214 offset:23328
	v_fmac_f32_e32 v24, v160, v11
	v_fmac_f32_e32 v204, v160, v43
	v_cvt_pk_bf16_f32 v215, v11, v43
	v_fma_f32 v24, -v161, v43, v24
	v_fmac_f32_e32 v204, v161, v11
	ds_write_b32 v185, v215 offset:23600
	v_fmac_f32_e32 v25, v160, v24
	v_fmac_f32_e32 v205, v160, v204
	v_cvt_pk_bf16_f32 v212, v24, v204
	v_fma_f32 v25, -v161, v204, v25
	v_fmac_f32_e32 v205, v161, v24
	ds_write_b32 v185, v212 offset:23872
	v_fmac_f32_e32 v26, v160, v25
	v_fmac_f32_e32 v206, v160, v205
	v_cvt_pk_bf16_f32 v213, v25, v205
	v_fma_f32 v26, -v161, v205, v26
	v_fmac_f32_e32 v206, v161, v25
	ds_write_b32 v185, v213 offset:24144
	v_fmac_f32_e32 v27, v160, v26
	v_fmac_f32_e32 v207, v160, v206
	v_cvt_pk_bf16_f32 v214, v26, v206
	v_fma_f32 v27, -v161, v206, v27
	v_fmac_f32_e32 v207, v161, v26
	ds_write_b32 v185, v214 offset:24416
	v_fmac_f32_e32 v12, v160, v27
	v_fmac_f32_e32 v44, v160, v207
	v_cvt_pk_bf16_f32 v215, v27, v207
	v_fma_f32 v12, -v161, v207, v12
	v_fmac_f32_e32 v44, v161, v27
	ds_write_b32 v185, v215 offset:24688
	v_fmac_f32_e32 v13, v160, v12
	v_fmac_f32_e32 v45, v160, v44
	v_cvt_pk_bf16_f32 v212, v12, v44
	v_fma_f32 v13, -v161, v44, v13
	v_fmac_f32_e32 v45, v161, v12
	ds_write_b32 v185, v212 offset:24960
	v_fmac_f32_e32 v14, v160, v13
	v_fmac_f32_e32 v46, v160, v45
	v_cvt_pk_bf16_f32 v213, v13, v45
	v_fma_f32 v14, -v161, v45, v14
	v_fmac_f32_e32 v46, v161, v13
	ds_write_b32 v185, v213 offset:25232
	v_fmac_f32_e32 v15, v160, v14
	v_fmac_f32_e32 v47, v160, v46
	v_cvt_pk_bf16_f32 v214, v14, v46
	v_fma_f32 v15, -v161, v46, v15
	v_fmac_f32_e32 v47, v161, v14
	ds_write_b32 v185, v214 offset:25504
	v_fmac_f32_e32 v28, v160, v15
	v_fmac_f32_e32 v208, v160, v47
	v_cvt_pk_bf16_f32 v215, v15, v47
	v_fma_f32 v28, -v161, v47, v28
	v_fmac_f32_e32 v208, v161, v15
	ds_write_b32 v185, v215 offset:25776
	v_fmac_f32_e32 v29, v160, v28
	v_fmac_f32_e32 v209, v160, v208
	v_cvt_pk_bf16_f32 v212, v28, v208
	v_fma_f32 v29, -v161, v208, v29
	v_fmac_f32_e32 v209, v161, v28
	ds_write_b32 v185, v212 offset:26048
	v_fmac_f32_e32 v30, v160, v29
	v_fmac_f32_e32 v210, v160, v209
	v_cvt_pk_bf16_f32 v213, v29, v209
	v_fma_f32 v30, -v161, v209, v30
	v_fmac_f32_e32 v210, v161, v29
	ds_write_b32 v185, v213 offset:26320
	v_fmac_f32_e32 v31, v160, v30
	v_fmac_f32_e32 v211, v160, v210
	v_cvt_pk_bf16_f32 v214, v30, v210
	v_fma_f32 v31, -v161, v210, v31
	v_fmac_f32_e32 v211, v161, v30
	ds_write_b32 v185, v214 offset:26592
	v_mov_b32_e32 v188, v31
	v_mov_b32_e32 v189, v211
	v_cvt_pk_bf16_f32 v215, v31, v211
	ds_write_b32 v185, v215 offset:26864
	s_waitcnt lgkmcnt(0)
	ds_read_b128 v[32:35], v186 offset:18432
	ds_read_b128 v[36:39], v186 offset:18464
	ds_read_b128 v[40:43], v186 offset:18496
	ds_read_b128 v[44:47], v186 offset:18528
	ds_read_b128 v[196:199], v186 offset:18560
	ds_read_b128 v[200:203], v186 offset:18592
	ds_read_b128 v[204:207], v186 offset:18624
	ds_read_b128 v[208:211], v186 offset:18656
	s_waitcnt lgkmcnt(7)
	v_mfma_f32_32x32x16_bf16 v[48:63], v[64:67], v[32:35], 0
	v_fmac_f32_e32 v234, v100, v162
	v_fmac_f32_e32 v235, v101, v163
	v_fmac_f32_e32 v236, v102, v164
	v_fmac_f32_e32 v237, v103, v165
	v_fmac_f32_e32 v238, v80, v166
	v_fmac_f32_e32 v239, v81, v167
	v_fmac_f32_e32 v240, v82, v192
	v_fmac_f32_e32 v241, v83, v193
	v_mul_f32_e32 v242, v234, v234
	s_waitcnt lgkmcnt(6)
	v_mfma_f32_32x32x16_bf16 v[48:63], v[68:71], v[36:39], v[48:63]
	v_mul_f32_e32 v243, v235, v235
	v_mul_f32_e32 v244, v236, v236
	v_mul_f32_e32 v245, v237, v237
	v_mul_f32_e32 v246, v238, v238
	v_mul_f32_e32 v247, v239, v239
	v_mul_f32_e32 v248, v240, v240
	v_mul_f32_e32 v249, v241, v241
	v_fmaak_f32 v242, v242, v184, 0xc0135761
	v_fmaak_f32 v243, v243, v184, 0xc0135761
	s_waitcnt lgkmcnt(5)
	v_mfma_f32_32x32x16_bf16 v[48:63], v[72:75], v[40:43], v[48:63]
	v_fmaak_f32 v244, v244, v184, 0xc0135761
	v_fmaak_f32 v245, v245, v184, 0xc0135761
	v_fmaak_f32 v246, v246, v184, 0xc0135761
	v_fmaak_f32 v247, v247, v184, 0xc0135761
	v_fmaak_f32 v248, v248, v184, 0xc0135761
	v_fmaak_f32 v249, v249, v184, 0xc0135761
	v_mul_f32_e32 v242, v234, v242
	v_mul_f32_e32 v243, v235, v243
	v_mul_f32_e32 v244, v236, v244
	s_waitcnt lgkmcnt(4)
	v_mfma_f32_32x32x16_bf16 v[48:63], v[76:79], v[44:47], v[48:63]
	v_mul_f32_e32 v245, v237, v245
	v_mul_f32_e32 v246, v238, v246
	v_mul_f32_e32 v247, v239, v247
	v_mul_f32_e32 v248, v240, v248
	v_mul_f32_e32 v249, v241, v249
	v_exp_f32_e32 v242, v242
	v_exp_f32_e32 v243, v243
	v_exp_f32_e32 v244, v244
	v_exp_f32_e32 v245, v245
	s_waitcnt lgkmcnt(3)
	v_mfma_f32_32x32x16_bf16 v[48:63], v[84:87], v[196:199], v[48:63]
	v_exp_f32_e32 v246, v246
	v_exp_f32_e32 v247, v247
	v_exp_f32_e32 v248, v248
	v_exp_f32_e32 v249, v249
	v_add_f32_e32 v242, 1.0, v242
	v_add_f32_e32 v243, 1.0, v243
	v_add_f32_e32 v244, 1.0, v244
	v_add_f32_e32 v245, 1.0, v245
	s_waitcnt lgkmcnt(2)
	v_mfma_f32_32x32x16_bf16 v[48:63], v[88:91], v[200:203], v[48:63]
	v_add_f32_e32 v246, 1.0, v246
	v_add_f32_e32 v247, 1.0, v247
	v_add_f32_e32 v248, 1.0, v248
	v_add_f32_e32 v249, 1.0, v249
	v_rcp_f32_e32 v242, v242
	v_rcp_f32_e32 v243, v243
	v_rcp_f32_e32 v244, v244
	v_rcp_f32_e32 v245, v245
	s_waitcnt lgkmcnt(1)
	v_mfma_f32_32x32x16_bf16 v[48:63], v[96:99], v[204:207], v[48:63]
	v_rcp_f32_e32 v246, v246
	v_rcp_f32_e32 v247, v247
	v_rcp_f32_e32 v248, v248
	v_rcp_f32_e32 v249, v249
	v_mul_f32_e32 v234, v234, v242
	v_mul_f32_e32 v235, v235, v243
	v_mul_f32_e32 v236, v236, v244
	v_mul_f32_e32 v237, v237, v245
	s_waitcnt lgkmcnt(0)
	v_mfma_f32_32x32x16_bf16 v[48:63], v[108:111], v[208:211], v[48:63]
	v_mul_f32_e32 v238, v238, v246
	v_mul_f32_e32 v239, v239, v247
	v_mul_f32_e32 v240, v240, v248
	v_mul_f32_e32 v241, v241, v249
	v_cvt_pk_bf16_f32 v242, v234, v235
	v_cvt_pk_bf16_f32 v243, v236, v237
	v_cvt_pk_bf16_f32 v244, v238, v239
	v_cvt_pk_bf16_f32 v245, v240, v241
	global_store_dwordx2 v190, v[242:243], s[90:91]
	global_store_dwordx2 v191, v[244:245], s[90:91]
	s_add_i32 s2, s2, 32
	v_add_u32_e32 v187, 4, v187
	s_cmp_lt_u32 s16, 0x2800
	s_cbranch_scc1 .Lscan_w3_3
	s_waitcnt vmcnt(11)
	s_branch .Lscan_go_3

.Lscan_go_3:
	v_mfma_f32_32x32x16_bf16 v[0:15], v[178:181], v[104:107], 0
	s_and_b32 s18, s16, 0x2000
	s_and_b32 s17, s2, 0x1f00
	s_or_b32 s17, s17, s13
	s_lshl_b32 s17, s17, 12
	s_and_b32 s17, s17, 0x1ffc000
	s_addk_i32 s16, 0x800
	v_mfma_f32_32x32x16_bf16 v[16:31], v[178:181], v[116:119], 0
	v_add_u32_e32 v222, s2, v174
	v_and_or_b32 v223, v187, 14, s4
	v_lshlrev_b32_e32 v225, 5, v222
	v_lshlrev_b32_e32 v226, 1, v222
	v_lshl_or_b32 v227, v223, 9, s18
	v_and_b32_e32 v222, 0x1e0, v225
	v_mfma_f32_32x32x16_bf16 v[32:47], v[178:181], v[92:95], 0
	v_and_b32_e32 v223, 16, v226
	v_or_b32_e32 v224, v222, v132
	v_bitop3_b32 v222, v222, v223, v132 bitop3:0x36
	v_or_b32_e32 v225, s17, v227
	v_bitop3_b32 v226, v224, v223, 8 bitop3:0x36
	v_or_b32_e32 v227, v222, v225
	v_mfma_f32_32x32x16_bf16 v[196:211], v[178:181], v[112:115], 0
	v_mov_b32_e32 v218, v178
	v_mov_b32_e32 v219, v179
	v_mov_b32_e32 v220, v180
	v_mov_b32_e32 v221, v181
	s_nop 0
	v_permlane32_swap_b32_e32 v218, v220
	v_permlane32_swap_b32_e32 v219, v221
	s_add_u32 s0, s0, 0x40000
	s_addc_u32 s1, s1, 0
	v_lshl_add_u64 v[216:217], v[152:153], 0, s[0:1]
	global_load_dwordx4 v[178:181], v[216:217], off
	v_lshlrev_b32_e32 v162, 16, v218
	v_and_b32_e32 v163, 0xffff0000, v218
	v_lshlrev_b32_e32 v164, 16, v219
	v_and_b32_e32 v165, 0xffff0000, v219
	v_lshlrev_b32_e32 v166, 16, v220
	v_and_b32_e32 v167, 0xffff0000, v220
	v_lshlrev_b32_e32 v192, 16, v221
	v_and_b32_e32 v193, 0xffff0000, v221
	v_or_b32_e32 v191, v226, v225
	v_lshlrev_b32_e32 v190, 1, v227
	v_lshlrev_b32_e32 v191, 1, v191
	v_permlane32_swap_b32_e32 v0, v16
	v_permlane32_swap_b32_e32 v1, v17
	v_permlane32_swap_b32_e32 v2, v18
	v_permlane32_swap_b32_e32 v3, v19
	v_permlane32_swap_b32_e32 v4, v20
	v_permlane32_swap_b32_e32 v5, v21
	v_permlane32_swap_b32_e32 v6, v22
	v_permlane32_swap_b32_e32 v7, v23
	v_permlane32_swap_b32_e32 v8, v24
	v_permlane32_swap_b32_e32 v9, v25
	v_permlane32_swap_b32_e32 v10, v26
	v_permlane32_swap_b32_e32 v11, v27
	v_permlane32_swap_b32_e32 v12, v28
	v_permlane32_swap_b32_e32 v13, v29
	v_permlane32_swap_b32_e32 v14, v30
	v_permlane32_swap_b32_e32 v15, v31
	v_permlane32_swap_b32_e32 v32, v196
	v_permlane32_swap_b32_e32 v33, v197
	v_permlane32_swap_b32_e32 v34, v198
	v_permlane32_swap_b32_e32 v35, v199
	v_permlane32_swap_b32_e32 v36, v200
	v_permlane32_swap_b32_e32 v37, v201
	v_permlane32_swap_b32_e32 v38, v202
	v_permlane32_swap_b32_e32 v39, v203
	v_permlane32_swap_b32_e32 v40, v204
	v_permlane32_swap_b32_e32 v41, v205
	v_permlane32_swap_b32_e32 v42, v206
	v_permlane32_swap_b32_e32 v43, v207
	v_permlane32_swap_b32_e32 v44, v208
	v_permlane32_swap_b32_e32 v45, v209
	v_permlane32_swap_b32_e32 v46, v210
	v_permlane32_swap_b32_e32 v47, v211
	v_fmac_f32_e32 v0, v160, v188
	v_fmac_f32_e32 v32, v160, v189
	v_fma_f32 v0, -v161, v189, v0
	v_fmac_f32_e32 v32, v161, v188
	v_fmac_f32_e32 v1, v160, v0
	v_fmac_f32_e32 v33, v160, v32
	v_cvt_pk_bf16_f32 v212, v0, v32
	v_fma_f32 v1, -v161, v32, v1
	v_fmac_f32_e32 v33, v161, v0
	ds_write_b32 v185, v212 offset:18432
	v_fmac_f32_e32 v2, v160, v1
	v_fmac_f32_e32 v34, v160, v33
	v_cvt_pk_bf16_f32 v213, v1, v33
	v_fma_f32 v2, -v161, v33, v2
	v_fmac_f32_e32 v34, v161, v1
	ds_write_b32 v185, v213 offset:18704
	v_fmac_f32_e32 v3, v160, v2
	v_fmac_f32_e32 v35, v160, v34
	v_cvt_pk_bf16_f32 v214, v2, v34
	v_fma_f32 v3, -v161, v34, v3
	v_fmac_f32_e32 v35, v161, v2
	ds_write_b32 v185, v214 offset:18976
	v_fmac_f32_e32 v16, v160, v3
	v_fmac_f32_e32 v196, v160, v35
	v_cvt_pk_bf16_f32 v215, v3, v35
	v_fma_f32 v16, -v161, v35, v16
	v_fmac_f32_e32 v196, v161, v3
	ds_write_b32 v185, v215 offset:19248
	v_fmac_f32_e32 v17, v160, v16
	v_fmac_f32_e32 v197, v160, v196
	v_cvt_pk_bf16_f32 v212, v16, v196
	v_fma_f32 v17, -v161, v196, v17
	v_fmac_f32_e32 v197, v161, v16
	ds_write_b32 v185, v212 offset:19520
	v_fmac_f32_e32 v18, v160, v17
	v_fmac_f32_e32 v198, v160, v197
	v_cvt_pk_bf16_f32 v213, v17, v197
	v_fma_f32 v18, -v161, v197, v18
	v_fmac_f32_e32 v198, v161, v17
	ds_write_b32 v185, v213 offset:19792
	v_fmac_f32_e32 v19, v160, v18
	v_fmac_f32_e32 v199, v160, v198
	v_cvt_pk_bf16_f32 v214, v18, v198
	v_fma_f32 v19, -v161, v198, v19
	v_fmac_f32_e32 v199, v161, v18
	ds_write_b32 v185, v214 offset:20064
	v_fmac_f32_e32 v4, v160, v19
	v_fmac_f32_e32 v36, v160, v199
	v_cvt_pk_bf16_f32 v215, v19, v199
	v_fma_f32 v4, -v161, v199, v4
	v_fmac_f32_e32 v36, v161, v19
	ds_write_b32 v185, v215 offset:20336
	v_fmac_f32_e32 v5, v160, v4
	v_fmac_f32_e32 v37, v160, v36
	v_cvt_pk_bf16_f32 v212, v4, v36
	v_fma_f32 v5, -v161, v36, v5
	v_fmac_f32_e32 v37, v161, v4
	ds_write_b32 v185, v212 offset:20608
	v_fmac_f32_e32 v6, v160, v5
	v_fmac_f32_e32 v38, v160, v37
	v_cvt_pk_bf16_f32 v213, v5, v37
	v_fma_f32 v6, -v161, v37, v6
	v_fmac_f32_e32 v38, v161, v5
	ds_write_b32 v185, v213 offset:20880
	v_fmac_f32_e32 v7, v160, v6
	v_fmac_f32_e32 v39, v160, v38
	v_cvt_pk_bf16_f32 v214, v6, v38
	v_fma_f32 v7, -v161, v38, v7
	v_fmac_f32_e32 v39, v161, v6
	ds_write_b32 v185, v214 offset:21152
	v_fmac_f32_e32 v20, v160, v7
	v_fmac_f32_e32 v200, v160, v39
	v_cvt_pk_bf16_f32 v215, v7, v39
	v_fma_f32 v20, -v161, v39, v20
	v_fmac_f32_e32 v200, v161, v7
	ds_write_b32 v185, v215 offset:21424
	v_fmac_f32_e32 v21, v160, v20
	v_fmac_f32_e32 v201, v160, v200
	v_cvt_pk_bf16_f32 v212, v20, v200
	v_fma_f32 v21, -v161, v200, v21
	v_fmac_f32_e32 v201, v161, v20
	ds_write_b32 v185, v212 offset:21696
	v_fmac_f32_e32 v22, v160, v21
	v_fmac_f32_e32 v202, v160, v201
	v_cvt_pk_bf16_f32 v213, v21, v201
	v_fma_f32 v22, -v161, v201, v22
	v_fmac_f32_e32 v202, v161, v21
	ds_write_b32 v185, v213 offset:21968
	v_fmac_f32_e32 v23, v160, v22
	v_fmac_f32_e32 v203, v160, v202
	v_cvt_pk_bf16_f32 v214, v22, v202
	v_fma_f32 v23, -v161, v202, v23
	v_fmac_f32_e32 v203, v161, v22
	ds_write_b32 v185, v214 offset:22240
	v_fmac_f32_e32 v8, v160, v23
	v_fmac_f32_e32 v40, v160, v203
	v_cvt_pk_bf16_f32 v215, v23, v203
	v_fma_f32 v8, -v161, v203, v8
	v_fmac_f32_e32 v40, v161, v23
	ds_write_b32 v185, v215 offset:22512
	v_fmac_f32_e32 v9, v160, v8
	v_fmac_f32_e32 v41, v160, v40
	v_cvt_pk_bf16_f32 v212, v8, v40
	v_fma_f32 v9, -v161, v40, v9
	v_fmac_f32_e32 v41, v161, v8
	ds_write_b32 v185, v212 offset:22784
	v_fmac_f32_e32 v10, v160, v9
	v_fmac_f32_e32 v42, v160, v41
	v_cvt_pk_bf16_f32 v213, v9, v41
	v_fma_f32 v10, -v161, v41, v10
	v_fmac_f32_e32 v42, v161, v9
	ds_write_b32 v185, v213 offset:23056
	v_fmac_f32_e32 v11, v160, v10
	v_fmac_f32_e32 v43, v160, v42
	v_cvt_pk_bf16_f32 v214, v10, v42
	v_fma_f32 v11, -v161, v42, v11
	v_fmac_f32_e32 v43, v161, v10
	ds_write_b32 v185, v214 offset:23328
	v_fmac_f32_e32 v24, v160, v11
	v_fmac_f32_e32 v204, v160, v43
	v_cvt_pk_bf16_f32 v215, v11, v43
	v_fma_f32 v24, -v161, v43, v24
	v_fmac_f32_e32 v204, v161, v11
	ds_write_b32 v185, v215 offset:23600
	v_fmac_f32_e32 v25, v160, v24
	v_fmac_f32_e32 v205, v160, v204
	v_cvt_pk_bf16_f32 v212, v24, v204
	v_fma_f32 v25, -v161, v204, v25
	v_fmac_f32_e32 v205, v161, v24
	ds_write_b32 v185, v212 offset:23872
	v_fmac_f32_e32 v26, v160, v25
	v_fmac_f32_e32 v206, v160, v205
	v_cvt_pk_bf16_f32 v213, v25, v205
	v_fma_f32 v26, -v161, v205, v26
	v_fmac_f32_e32 v206, v161, v25
	ds_write_b32 v185, v213 offset:24144
	v_fmac_f32_e32 v27, v160, v26
	v_fmac_f32_e32 v207, v160, v206
	v_cvt_pk_bf16_f32 v214, v26, v206
	v_fma_f32 v27, -v161, v206, v27
	v_fmac_f32_e32 v207, v161, v26
	ds_write_b32 v185, v214 offset:24416
	v_fmac_f32_e32 v12, v160, v27
	v_fmac_f32_e32 v44, v160, v207
	v_cvt_pk_bf16_f32 v215, v27, v207
	v_fma_f32 v12, -v161, v207, v12
	v_fmac_f32_e32 v44, v161, v27
	ds_write_b32 v185, v215 offset:24688
	v_fmac_f32_e32 v13, v160, v12
	v_fmac_f32_e32 v45, v160, v44
	v_cvt_pk_bf16_f32 v212, v12, v44
	v_fma_f32 v13, -v161, v44, v13
	v_fmac_f32_e32 v45, v161, v12
	ds_write_b32 v185, v212 offset:24960
	v_fmac_f32_e32 v14, v160, v13
	v_fmac_f32_e32 v46, v160, v45
	v_cvt_pk_bf16_f32 v213, v13, v45
	v_fma_f32 v14, -v161, v45, v14
	v_fmac_f32_e32 v46, v161, v13
	ds_write_b32 v185, v213 offset:25232
	v_fmac_f32_e32 v15, v160, v14
	v_fmac_f32_e32 v47, v160, v46
	v_cvt_pk_bf16_f32 v214, v14, v46
	v_fma_f32 v15, -v161, v46, v15
	v_fmac_f32_e32 v47, v161, v14
	ds_write_b32 v185, v214 offset:25504
	v_fmac_f32_e32 v28, v160, v15
	v_fmac_f32_e32 v208, v160, v47
	v_cvt_pk_bf16_f32 v215, v15, v47
	v_fma_f32 v28, -v161, v47, v28
	v_fmac_f32_e32 v208, v161, v15
	ds_write_b32 v185, v215 offset:25776
	v_fmac_f32_e32 v29, v160, v28
	v_fmac_f32_e32 v209, v160, v208
	v_cvt_pk_bf16_f32 v212, v28, v208
	v_fma_f32 v29, -v161, v208, v29
	v_fmac_f32_e32 v209, v161, v28
	ds_write_b32 v185, v212 offset:26048
	v_fmac_f32_e32 v30, v160, v29
	v_fmac_f32_e32 v210, v160, v209
	v_cvt_pk_bf16_f32 v213, v29, v209
	v_fma_f32 v30, -v161, v209, v30
	v_fmac_f32_e32 v210, v161, v29
	ds_write_b32 v185, v213 offset:26320
	v_fmac_f32_e32 v31, v160, v30
	v_fmac_f32_e32 v211, v160, v210
	v_cvt_pk_bf16_f32 v214, v30, v210
	v_fma_f32 v31, -v161, v210, v31
	v_fmac_f32_e32 v211, v161, v30
	ds_write_b32 v185, v214 offset:26592
	v_mov_b32_e32 v188, v31
	v_mov_b32_e32 v189, v211
	v_cvt_pk_bf16_f32 v215, v31, v211
	ds_write_b32 v185, v215 offset:26864
	s_waitcnt lgkmcnt(0)
	ds_read_b128 v[32:35], v186 offset:18432
	ds_read_b128 v[36:39], v186 offset:18464
	ds_read_b128 v[40:43], v186 offset:18496
	ds_read_b128 v[44:47], v186 offset:18528
	ds_read_b128 v[196:199], v186 offset:18560
	ds_read_b128 v[200:203], v186 offset:18592
	ds_read_b128 v[204:207], v186 offset:18624
	ds_read_b128 v[208:211], v186 offset:18656
	s_waitcnt lgkmcnt(7)
	v_mfma_f32_32x32x16_bf16 v[234:249], v[64:67], v[32:35], 0
	v_fmac_f32_e32 v48, v100, v228
	v_fmac_f32_e32 v49, v101, v229
	v_fmac_f32_e32 v50, v102, v230
	v_fmac_f32_e32 v51, v103, v231
	v_fmac_f32_e32 v52, v80, v232
	v_fmac_f32_e32 v53, v81, v233
	v_fmac_f32_e32 v54, v82, v251
	v_fmac_f32_e32 v55, v83, v252
	v_mul_f32_e32 v56, v48, v48
	s_waitcnt lgkmcnt(6)
	v_mfma_f32_32x32x16_bf16 v[234:249], v[68:71], v[36:39], v[234:249]
	v_mul_f32_e32 v57, v49, v49
	v_mul_f32_e32 v58, v50, v50
	v_mul_f32_e32 v59, v51, v51
	v_mul_f32_e32 v60, v52, v52
	v_mul_f32_e32 v61, v53, v53
	v_mul_f32_e32 v62, v54, v54
	v_mul_f32_e32 v63, v55, v55
	v_fmaak_f32 v56, v56, v184, 0xc0135761
	v_fmaak_f32 v57, v57, v184, 0xc0135761
	s_waitcnt lgkmcnt(5)
	v_mfma_f32_32x32x16_bf16 v[234:249], v[72:75], v[40:43], v[234:249]
	v_fmaak_f32 v58, v58, v184, 0xc0135761
	v_fmaak_f32 v59, v59, v184, 0xc0135761
	v_fmaak_f32 v60, v60, v184, 0xc0135761
	v_fmaak_f32 v61, v61, v184, 0xc0135761
	v_fmaak_f32 v62, v62, v184, 0xc0135761
	v_fmaak_f32 v63, v63, v184, 0xc0135761
	v_mul_f32_e32 v56, v48, v56
	v_mul_f32_e32 v57, v49, v57
	v_mul_f32_e32 v58, v50, v58
	s_waitcnt lgkmcnt(4)
	v_mfma_f32_32x32x16_bf16 v[234:249], v[76:79], v[44:47], v[234:249]
	v_mul_f32_e32 v59, v51, v59
	v_mul_f32_e32 v60, v52, v60
	v_mul_f32_e32 v61, v53, v61
	v_mul_f32_e32 v62, v54, v62
	v_mul_f32_e32 v63, v55, v63
	v_exp_f32_e32 v56, v56
	v_exp_f32_e32 v57, v57
	v_exp_f32_e32 v58, v58
	v_exp_f32_e32 v59, v59
	s_waitcnt lgkmcnt(3)
	v_mfma_f32_32x32x16_bf16 v[234:249], v[84:87], v[196:199], v[234:249]
	v_exp_f32_e32 v60, v60
	v_exp_f32_e32 v61, v61
	v_exp_f32_e32 v62, v62
	v_exp_f32_e32 v63, v63
	v_add_f32_e32 v56, 1.0, v56
	v_add_f32_e32 v57, 1.0, v57
	v_add_f32_e32 v58, 1.0, v58
	v_add_f32_e32 v59, 1.0, v59
	s_waitcnt lgkmcnt(2)
	v_mfma_f32_32x32x16_bf16 v[234:249], v[88:91], v[200:203], v[234:249]
	v_add_f32_e32 v60, 1.0, v60
	v_add_f32_e32 v61, 1.0, v61
	v_add_f32_e32 v62, 1.0, v62
	v_add_f32_e32 v63, 1.0, v63
	v_rcp_f32_e32 v56, v56
	v_rcp_f32_e32 v57, v57
	v_rcp_f32_e32 v58, v58
	v_rcp_f32_e32 v59, v59
	s_waitcnt lgkmcnt(1)
	v_mfma_f32_32x32x16_bf16 v[234:249], v[96:99], v[204:207], v[234:249]
	v_rcp_f32_e32 v60, v60
	v_rcp_f32_e32 v61, v61
	v_rcp_f32_e32 v62, v62
	v_rcp_f32_e32 v63, v63
	v_mul_f32_e32 v48, v48, v56
	v_mul_f32_e32 v49, v49, v57
	v_mul_f32_e32 v50, v50, v58
	v_mul_f32_e32 v51, v51, v59
	s_waitcnt lgkmcnt(0)
	v_mfma_f32_32x32x16_bf16 v[234:249], v[108:111], v[208:211], v[234:249]
	v_mul_f32_e32 v52, v52, v60
	v_mul_f32_e32 v53, v53, v61
	v_mul_f32_e32 v54, v54, v62
	v_mul_f32_e32 v55, v55, v63
	v_cvt_pk_bf16_f32 v56, v48, v49
	v_cvt_pk_bf16_f32 v57, v50, v51
	v_cvt_pk_bf16_f32 v58, v52, v53
	v_cvt_pk_bf16_f32 v59, v54, v55
	global_store_dwordx2 v253, v[56:57], s[90:91]
	global_store_dwordx2 v254, v[58:59], s[90:91]
	s_add_i32 s2, s2, 32
	v_add_u32_e32 v187, 4, v187
	s_cmp_eq_u32 s0, 0x1080000
	s_cbranch_scc0 .Lscan_tile
	s_nop 11
	v_fmac_f32_e32 v234, v100, v162
	v_fmac_f32_e32 v235, v101, v163
	v_fmac_f32_e32 v236, v102, v164
	v_fmac_f32_e32 v237, v103, v165
	v_fmac_f32_e32 v238, v80, v166
	v_fmac_f32_e32 v239, v81, v167
	v_fmac_f32_e32 v240, v82, v192
	v_fmac_f32_e32 v241, v83, v193
	v_mul_f32_e32 v242, v234, v234
	v_mul_f32_e32 v243, v235, v235
	v_mul_f32_e32 v244, v236, v236
	v_mul_f32_e32 v245, v237, v237
	v_mul_f32_e32 v246, v238, v238
	v_mul_f32_e32 v247, v239, v239
	v_mul_f32_e32 v248, v240, v240
	v_mul_f32_e32 v249, v241, v241
	v_fmaak_f32 v242, v242, v184, 0xc0135761
	v_fmaak_f32 v243, v243, v184, 0xc0135761
	v_fmaak_f32 v244, v244, v184, 0xc0135761
	v_fmaak_f32 v245, v245, v184, 0xc0135761
	v_fmaak_f32 v246, v246, v184, 0xc0135761
	v_fmaak_f32 v247, v247, v184, 0xc0135761
	v_fmaak_f32 v248, v248, v184, 0xc0135761
	v_fmaak_f32 v249, v249, v184, 0xc0135761
	v_mul_f32_e32 v242, v234, v242
	v_mul_f32_e32 v243, v235, v243
	v_mul_f32_e32 v244, v236, v244
	v_mul_f32_e32 v245, v237, v245
	v_mul_f32_e32 v246, v238, v246
	v_mul_f32_e32 v247, v239, v247
	v_mul_f32_e32 v248, v240, v248
	v_mul_f32_e32 v249, v241, v249
	v_exp_f32_e32 v242, v242
	v_exp_f32_e32 v243, v243
	v_exp_f32_e32 v244, v244
	v_exp_f32_e32 v245, v245
	v_exp_f32_e32 v246, v246
	v_exp_f32_e32 v247, v247
	v_exp_f32_e32 v248, v248
	v_exp_f32_e32 v249, v249
	v_add_f32_e32 v242, 1.0, v242
	v_add_f32_e32 v243, 1.0, v243
	v_add_f32_e32 v244, 1.0, v244
	v_add_f32_e32 v245, 1.0, v245
	v_add_f32_e32 v246, 1.0, v246
	v_add_f32_e32 v247, 1.0, v247
	v_add_f32_e32 v248, 1.0, v248
	v_add_f32_e32 v249, 1.0, v249
	v_rcp_f32_e32 v242, v242
	v_rcp_f32_e32 v243, v243
	v_rcp_f32_e32 v244, v244
	v_rcp_f32_e32 v245, v245
	v_rcp_f32_e32 v246, v246
	v_rcp_f32_e32 v247, v247
	v_rcp_f32_e32 v248, v248
	v_rcp_f32_e32 v249, v249
	v_mul_f32_e32 v234, v234, v242
	v_mul_f32_e32 v235, v235, v243
	v_mul_f32_e32 v236, v236, v244
	v_mul_f32_e32 v237, v237, v245
	v_mul_f32_e32 v238, v238, v246
	v_mul_f32_e32 v239, v239, v247
	v_mul_f32_e32 v240, v240, v248
	v_mul_f32_e32 v241, v241, v249
	v_cvt_pk_bf16_f32 v242, v234, v235
	v_cvt_pk_bf16_f32 v243, v236, v237
	v_cvt_pk_bf16_f32 v244, v238, v239
	v_cvt_pk_bf16_f32 v245, v240, v241
	global_store_dwordx2 v190, v[242:243], s[90:91]
	global_store_dwordx2 v191, v[244:245], s[90:91]
	s_add_i32 s6, s6, s7
	s_add_i32 s10, s10, s11
	s_add_i32 s12, s12, s7
	s_cmpk_gt_i32 s6, 0x3ff
	s_cbranch_scc0 .LBB0_563
